# attention loop: cross-iteration pipeline, K and V rings decoupled (two barriers per tile), uniform 12-MFMA steps
# speedup vs baseline: 1.0145x; 1.0145x over previous
; __device__ __forceinline__ void attn_item(const P& p, int layer, int item, char* lds) {
;   const int tid = ltid(), wid = tid >> 6, lane = tid & 63, r32 = lane & 31, hi = lane >> 5;
;   const int qb = item & 63, h = (item >> 6) & 3, b = item >> 8;
;   const u16* z = (const u16*)(p.ws + OFF_Z);
;   const long tokb = (long)b * SEQ, tokq = tokb + qb * 128;
;   constexpr int STG = 2 * ATT_KB + ATT_VB;
;   float* wsf = (float*)(lds + 2 * STG) + wid * 64;
;   float* li_l = wsf; float* al_l = wsf + 32;
;   const int vb0 = (int)(uintptr_t)(lds + 2 * ATT_KB) + v_rd_base(lane);
;   const int koff = r32 * 128, ksw = (r32 >> 1) & 7;
;   const unsigned k_src = (tid >> 3) * ZC + (((tid & 7) ^ ((tid >> 4) & 7)) << 3);
;   const int v_kl = (tid & 31) >> 2;
;   const unsigned v_src = (v_kl | ((tid >> 7) << 3)) * ZC + ((tid >> 5) & 3) * 32 + (tid & 3) * 8;
;   char* lw = lds + tid * 16;
;   const float lam = ((const float*)(p.ws + OFF_LAM))[layer];
;   const u16* Kg = z + tokb * ZC + C_DAK + h * 128; const u16* Vg = z + tokb * ZC + C_DAV + h * 128;
;   bf16x8 q1[4], q2[2];
;   char* Qp = lds + 2 * STG + 1024 + tid * 16;
; #pragma unroll
;   for (int d0 = 0; d0 < 4; ++d0) q1[d0] = *(const bf16x8*)(z + (tokq + wid * 32 + r32) * ZC + h * 128 + d0 * 16 + hi * 8);
; #pragma unroll
;   for (int d0 = 0; d0 < 2; ++d0) q2[d0] = *(const bf16x8*)(z + (tokq + wid * 32 + r32) * ZC + h * 128 + 64 + d0 * 16 + hi * 8);
;   __syncthreads();
;   float qs1 = 0.f, qs2 = 0.f;
; #pragma unroll
;   for (int d0 = 0; d0 < 4; ++d0) qs1 += sumsq8(q1[d0]);
; #pragma unroll
;   for (int d0 = 0; d0 < 2; ++d0) qs2 += sumsq8(q2[d0]);
; #pragma unroll
;   for (int d0 = 2; d0 < 4; ++d0) { const bf16x8 t = *(const bf16x8*)(z + (tokq + wid * 32 + r32) * ZC + h * 128 + 64 + d0 * 16 + hi * 8);
;     qs2 += sumsq8(t); *(bf16x8*)(Qp + (d0 - 2) * 4096) = t; }
;   { auto rr = __builtin_amdgcn_permlane32_swap(__float_as_uint(qs1), __float_as_uint(qs1), false, false); qs1 = __uint_as_float(rr[0]) + __uint_as_float(rr[1]); }
;   { auto rr = __builtin_amdgcn_permlane32_swap(__float_as_uint(qs2), __float_as_uint(qs2), false, false); qs2 = __uint_as_float(rr[0]) + __uint_as_float(rr[1]); }
;   float mC1, mC2;
;   { const float* kmx = (const float*)(p.ws + OFF_KMX) + (size_t)((b * 4 + h) * 2) * 128;
;     float k1 = fmaxf(kmx[lane], kmx[64 + lane]), k2 = fmaxf(kmx[128 + lane], kmx[192 + lane]);
.LBB0_271:
	s_lshl_b32 s3, s83, 3
	s_and_b32 s3, s3, 0xfffffe00
	v_readlane_b32 s6, v253, 38
	s_or_b32 s8, s3, s6
	v_mov_b32_e32 v214, v229
	s_ashr_i32 s6, s8, 8
	s_ashr_i32 s7, s6, 31
	s_lshl_b32 s3, s83, 7
	s_waitcnt vmcnt(7)
	v_ashrrev_i32_e32 v0, 1, v214
	s_lshl_b64 s[70:71], s[6:7], 13
	s_and_b32 s3, s3, 0x1f80
	v_and_b32_e32 v202, 0xffffffe0, v0
	s_or_b32 s70, s70, s3
	v_ashrrev_i32_e32 v203, 31, v202
	v_and_b32_e32 v226, 31, v214
	v_lshl_add_u64 v[0:1], s[70:71], 0, v[202:203]
	v_or_b32_e32 v0, v0, v226
	v_mov_b64_e32 v[2:3], s[58:59]
	v_bfe_u32 v227, v214, 5, 1
	v_mad_u64_u32 v[2:3], s[18:19], v0, s9, v[2:3]
	v_mad_i32_i24 v3, v1, s9, v3
	v_lshlrev_b32_e32 v200, 4, v227
	v_lshl_add_u64 v[0:1], v[2:3], 0, v[200:201]
	global_load_dwordx4 v[180:183], v[0:1], off
	global_load_dwordx4 v[176:179], v[0:1], off offset:32
	global_load_dwordx4 v[172:175], v[0:1], off offset:64
	global_load_dword v225, v201, s[42:43]
	global_load_dwordx4 v[168:171], v[0:1], off offset:96
	global_load_dwordx4 v[164:167], v[0:1], off offset:128
	global_load_dwordx4 v[160:163], v[0:1], off offset:160
	v_lshlrev_b32_e32 v2, 1, v214
	s_waitcnt vmcnt(13)
	v_lshrrev_b32_e32 v4, 4, v214
	v_lshrrev_b32_e32 v3, 3, v214
	v_bfe_u32 v6, v214, 2, 3
	s_waitcnt vmcnt(12)
	v_ashrrev_i32_e32 v8, 4, v214
	v_and_b32_e32 v11, 32, v2
	v_xor_b32_e32 v2, v4, v214
	s_mov_b32 s3, 0xfffff8
	s_movk_i32 s33, 0xb00
	v_and_or_b32 v4, v8, s3, v6
	v_mul_lo_u32 v3, v3, s33
	s_waitcnt vmcnt(11)
	v_lshlrev_b32_e32 v14, 3, v2
	v_mul_u32_u24_e32 v2, 0xb00, v4
	v_and_or_b32 v4, v14, 56, v3
	s_barrier
	global_load_dwordx4 v[14:17], v[0:1], off offset:192
	s_mul_i32 s7, s6, 0x2c00000
	s_mul_hi_i32 s3, s6, 0x2c00000
	s_add_u32 s76, s58, s7
	s_addc_u32 s77, s59, s3
	s_ashr_i32 s6, s8, 5
	v_readlane_b32 s8, v253, 40
	s_or_b32 s18, s6, s8
	s_ashr_i32 s19, s18, 31
	s_lshl_b64 s[18:19], s[18:19], 9
	v_and_b32_e32 v228, 63, v214
	s_add_u32 s18, s73, s18
	s_addc_u32 s19, s80, s19
	v_lshlrev_b32_e32 v5, 4, v214
	v_and_b32_e32 v13, 0xc0, v5
	v_add_u32_e32 v232, 0, v5
	v_add_u32_e32 v230, 0x10400, v232
	s_mov_b32 s52, 0xf800000
	v_readfirstlane_b32 s8, v232
	s_mov_b32 m0, s8
	v_lshlrev_b32_e32 v10, 3, v214
	v_and_b32_e32 v7, 0x60, v214
	v_and_b32_e32 v12, 24, v10
	v_or3_b32 v2, v2, v7, v12
	s_cmp_lg_u32 0, -1
	v_lshrrev_b32_e32 v9, 1, v214
	s_mov_b32 s6, 0
	v_lshl_add_u32 v236, v226, 7, 0
	s_movk_i32 s11, 0xb00
	s_waitcnt vmcnt(7)
	v_and_b32_e32 v18, 0xffff0000, v180
	s_waitcnt vmcnt(6)
	v_and_b32_e32 v26, 0xffff0000, v176
	v_lshlrev_b32_e32 v3, 16, v180
	v_lshlrev_b32_e32 v25, 16, v176
	v_mul_f32_e32 v18, v18, v18
	v_mul_f32_e32 v26, v26, v26
	v_lshlrev_b32_e32 v19, 16, v181
	v_lshlrev_b32_e32 v27, 16, v177
	v_fmac_f32_e32 v18, v3, v3
	v_fmac_f32_e32 v26, v25, v25
	v_and_b32_e32 v20, 0xffff0000, v181
	v_and_b32_e32 v28, 0xffff0000, v177
	v_fmac_f32_e32 v18, v19, v19
	v_fmac_f32_e32 v26, v27, v27
	v_lshlrev_b32_e32 v21, 16, v182
	v_lshlrev_b32_e32 v29, 16, v178
	s_waitcnt vmcnt(5)
	v_and_b32_e32 v34, 0xffff0000, v172
	v_fmac_f32_e32 v18, v20, v20
	v_fmac_f32_e32 v26, v28, v28
	v_and_b32_e32 v22, 0xffff0000, v182
	v_and_b32_e32 v30, 0xffff0000, v178
	v_lshlrev_b32_e32 v33, 16, v172
	v_mul_f32_e32 v34, v34, v34
	v_fmac_f32_e32 v18, v21, v21
	v_fmac_f32_e32 v26, v29, v29
	v_lshlrev_b32_e32 v23, 16, v183
	v_lshlrev_b32_e32 v31, 16, v179
	v_lshlrev_b32_e32 v35, 16, v173
	v_fmac_f32_e32 v34, v33, v33
	v_fmac_f32_e32 v18, v22, v22
	v_fmac_f32_e32 v26, v30, v30
	v_and_b32_e32 v24, 0xffff0000, v183
	v_and_b32_e32 v32, 0xffff0000, v179
	v_and_b32_e32 v36, 0xffff0000, v173
	v_fmac_f32_e32 v34, v35, v35
	v_fmac_f32_e32 v18, v23, v23
	v_fmac_f32_e32 v26, v31, v31
	v_lshlrev_b32_e32 v37, 16, v174
	v_fmac_f32_e32 v34, v36, v36
	v_fmac_f32_e32 v18, v24, v24
	v_fmac_f32_e32 v26, v32, v32
	v_fmac_f32_e32 v34, v37, v37
	v_add_f32_e32 v3, v18, v26
	v_and_b32_e32 v18, 0xffff0000, v174
	v_fmac_f32_e32 v34, v18, v18
	v_lshlrev_b32_e32 v18, 16, v175
	v_fmac_f32_e32 v34, v18, v18
	v_and_b32_e32 v18, 0xffff0000, v175
	v_fmac_f32_e32 v34, v18, v18
	s_waitcnt vmcnt(3)
	v_and_b32_e32 v23, 0xffff0000, v168
	global_load_dwordx4 v[18:21], v[0:1], off offset:224
	v_lshlrev_b32_e32 v1, 2, v228
	v_mul_f32_e32 v0, v23, v23
	global_load_dword v23, v1, s[18:19] offset:256
	global_load_dword v24, v1, s[18:19] offset:512
	global_load_dword v25, v1, s[18:19] offset:768
	s_nop 0
	global_load_dword v1, v1, s[18:19]
	v_lshlrev_b32_e32 v22, 16, v168
	v_fmac_f32_e32 v0, v22, v22
	v_lshlrev_b32_e32 v22, 16, v169
	v_fmac_f32_e32 v0, v22, v22
	v_and_b32_e32 v22, 0xffff0000, v169
	v_fmac_f32_e32 v0, v22, v22
	v_lshlrev_b32_e32 v22, 16, v170
	v_fmac_f32_e32 v0, v22, v22
	v_and_b32_e32 v22, 0xffff0000, v170
	v_fmac_f32_e32 v0, v22, v22
	v_lshlrev_b32_e32 v22, 16, v171
	v_fmac_f32_e32 v0, v22, v22
	v_and_b32_e32 v22, 0xffff0000, v171
	v_add_f32_e32 v3, v3, v34
	v_fmac_f32_e32 v0, v22, v22
	s_waitcnt vmcnt(7)
	v_and_b32_e32 v5, 0xffff0000, v164
	v_add_f32_e32 v0, v3, v0
	v_lshlrev_b32_e32 v3, 16, v164
	v_mul_f32_e32 v5, v5, v5
	v_fmac_f32_e32 v5, v3, v3
	v_lshlrev_b32_e32 v3, 16, v165
	v_fmac_f32_e32 v5, v3, v3
	v_and_b32_e32 v3, 0xffff0000, v165
	v_fmac_f32_e32 v5, v3, v3
	v_lshlrev_b32_e32 v3, 16, v166
	v_fmac_f32_e32 v5, v3, v3
	v_and_b32_e32 v3, 0xffff0000, v166
	v_fmac_f32_e32 v5, v3, v3
	v_lshlrev_b32_e32 v3, 16, v167
	v_fmac_f32_e32 v5, v3, v3
	v_and_b32_e32 v3, 0xffff0000, v167
	s_waitcnt vmcnt(6)
; __device__ __forceinline__ void attn_item(const P& p, int layer, int item, char* lds) {
;     ...
;   for (int d0 = 0; d0 < 4; ++d0) qs1 += sumsq8(q1[d0]);
; #pragma unroll
;   for (int d0 = 0; d0 < 2; ++d0) qs2 += sumsq8(q2[d0]);
; #pragma unroll
;   for (int d0 = 2; d0 < 4; ++d0) { const bf16x8 t = *(const bf16x8*)(z + (tokq + wid * 32 + r32) * ZC + h * 128 + 64 + d0 * 16 + hi * 8);
;     qs2 += sumsq8(t); *(bf16x8*)(Qp + (d0 - 2) * 4096) = t; }
;   { auto rr = __builtin_amdgcn_permlane32_swap(__float_as_uint(qs1), __float_as_uint(qs1), false, false); qs1 = __uint_as_float(rr[0]) + __uint_as_float(rr[1]); }
;   { auto rr = __builtin_amdgcn_permlane32_swap(__float_as_uint(qs2), __float_as_uint(qs2), false, false); qs2 = __uint_as_float(rr[0]) + __uint_as_float(rr[1]); }
;   float mC1, mC2;
;   { const float* kmx = (const float*)(p.ws + OFF_KMX) + (size_t)((b * 4 + h) * 2) * 128;
;     float k1 = fmaxf(kmx[lane], kmx[64 + lane]), k2 = fmaxf(kmx[128 + lane], kmx[192 + lane]);
; #pragma unroll
;     for (int o = 32; o >= 1; o >>= 1) { k1 = fmaxf(k1, __shfl_xor(k1, o)); k2 = fmaxf(k2, __shfl_xor(k2, o)); }
;     mC1 = sqrtf(qs1 * k1) * 1.4426950408889634f; mC2 = sqrtf(qs2 * k2) * 1.4426950408889634f; }
;   float l1 = 0.f, l2 = 0.f;
;   f32x16 o1[4], o2[4];
; #pragma unroll
;   for (int d = 0; d < 4; ++d) { o1[d] = f32x16{}; o2[d] = f32x16{}; }
;     ...
;   __syncthreads();
;   ISSUE_T(0, 0);
	v_and_b32_e32 v22, 0xffff0000, v160
	v_fmac_f32_e32 v5, v3, v3
	v_lshlrev_b32_e32 v3, 16, v160
	v_mul_f32_e32 v22, v22, v22
	v_fmac_f32_e32 v22, v3, v3
	v_lshlrev_b32_e32 v3, 16, v161
	v_fmac_f32_e32 v22, v3, v3
	v_and_b32_e32 v3, 0xffff0000, v161
	v_fmac_f32_e32 v22, v3, v3
	v_lshlrev_b32_e32 v3, 16, v162
	v_fmac_f32_e32 v22, v3, v3
	v_and_b32_e32 v3, 0xffff0000, v162
	v_fmac_f32_e32 v22, v3, v3
	v_lshlrev_b32_e32 v3, 16, v163
	v_fmac_f32_e32 v22, v3, v3
	v_and_b32_e32 v3, 0xffff0000, v163
	v_fmac_f32_e32 v22, v3, v3
	v_add_f32_e32 v3, v5, v22
	s_waitcnt vmcnt(5)
	v_and_b32_e32 v22, 0xffff0000, v14
	v_lshlrev_b32_e32 v5, 16, v14
	v_mul_f32_e32 v22, v22, v22
	v_fmac_f32_e32 v22, v5, v5
	v_lshlrev_b32_e32 v5, 16, v15
	v_fmac_f32_e32 v22, v5, v5
	v_and_b32_e32 v5, 0xffff0000, v15
	v_fmac_f32_e32 v22, v5, v5
	v_lshlrev_b32_e32 v5, 16, v16
	v_fmac_f32_e32 v22, v5, v5
	v_and_b32_e32 v5, 0xffff0000, v16
	v_fmac_f32_e32 v22, v5, v5
	v_lshlrev_b32_e32 v5, 16, v17
	v_fmac_f32_e32 v22, v5, v5
	v_and_b32_e32 v5, 0xffff0000, v17
	v_fmac_f32_e32 v22, v5, v5
	ds_write_b128 v230, v[14:17]
	v_and_b32_e32 v17, 64, v250
	v_add_f32_e32 v3, v3, v22
	v_add_u32_e32 v17, 64, v17
	v_xor_b32_e32 v22, 32, v250
	v_cmp_lt_i32_e32 vcc, v22, v17
	s_mov_b64 s[18:19], 0x2c400
	s_waitcnt vmcnt(3)
	v_max_f32_e32 v15, v23, v23
	v_cndmask_b32_e32 v22, v250, v22, vcc
	v_lshlrev_b32_e32 v22, 2, v22
	s_waitcnt vmcnt(0)
	v_max_f32_e32 v1, v1, v1
	v_max_f32_e32 v1, v1, v15
	ds_bpermute_b32 v23, v22, v1
	v_max_f32_e32 v15, v25, v25
	v_max_f32_e32 v16, v24, v24
	v_max_f32_e32 v15, v16, v15
	ds_bpermute_b32 v16, v22, v15
	s_waitcnt lgkmcnt(1)
	v_max_f32_e32 v22, v23, v23
	v_max_f32_e32 v1, v1, v22
	v_xor_b32_e32 v22, 16, v250
	v_cmp_lt_i32_e32 vcc, v22, v17
	s_waitcnt lgkmcnt(0)
	v_max_f32_e32 v16, v16, v16
	v_max_f32_e32 v15, v15, v16
	v_cndmask_b32_e32 v22, v250, v22, vcc
	v_lshlrev_b32_e32 v203, 2, v22
	ds_bpermute_b32 v22, v203, v1
	v_and_b32_e32 v14, 0xffff0000, v18
	ds_bpermute_b32 v16, v203, v15
	v_lshlrev_b32_e32 v5, 16, v18
	v_mul_f32_e32 v14, v14, v14
	s_waitcnt lgkmcnt(1)
	v_max_f32_e32 v22, v22, v22
	v_fmac_f32_e32 v14, v5, v5
	v_lshlrev_b32_e32 v5, 16, v19
	v_max_f32_e32 v1, v1, v22
	v_xor_b32_e32 v22, 8, v250
	v_fmac_f32_e32 v14, v5, v5
	v_and_b32_e32 v5, 0xffff0000, v19
	v_cmp_lt_i32_e32 vcc, v22, v17
	v_fmac_f32_e32 v14, v5, v5
	v_lshlrev_b32_e32 v5, 16, v20
	v_cndmask_b32_e32 v22, v250, v22, vcc
	v_fmac_f32_e32 v14, v5, v5
	v_and_b32_e32 v5, 0xffff0000, v20
	s_waitcnt lgkmcnt(0)
	v_max_f32_e32 v16, v16, v16
	v_lshlrev_b32_e32 v252, 2, v22
	v_fmac_f32_e32 v14, v5, v5
	v_lshlrev_b32_e32 v5, 16, v21
	ds_bpermute_b32 v22, v252, v1
	v_max_f32_e32 v15, v15, v16
	v_fmac_f32_e32 v14, v5, v5
	v_and_b32_e32 v5, 0xffff0000, v21
	ds_bpermute_b32 v16, v252, v15
	v_fmac_f32_e32 v14, v5, v5
	v_add_f32_e32 v3, v3, v14
	v_xor_b32_e32 v14, 4, v250
	v_cmp_lt_i32_e32 vcc, v14, v17
	s_waitcnt lgkmcnt(1)
	v_max_f32_e32 v5, v22, v22
	v_max_f32_e32 v1, v1, v5
	v_cndmask_b32_e32 v14, v250, v14, vcc
	s_waitcnt lgkmcnt(0)
	v_max_f32_e32 v5, v16, v16
	v_lshlrev_b32_e32 v217, 2, v14
	ds_bpermute_b32 v14, v217, v1
	v_max_f32_e32 v5, v15, v5
	ds_bpermute_b32 v15, v217, v5
	v_mov_b32_e32 v16, v0
	s_nop 1
	v_permlane32_swap_b32_e32 v0, v16
	s_waitcnt lgkmcnt(1)
	v_max_f32_e32 v14, v14, v14
	v_max_f32_e32 v1, v1, v14
	s_waitcnt lgkmcnt(0)
	v_max_f32_e32 v14, v15, v15
	v_max_f32_e32 v5, v5, v14
	v_xor_b32_e32 v14, 2, v250
	v_cmp_lt_i32_e32 vcc, v14, v17
	v_add_f32_e32 v0, v0, v16
	ds_write_b128 v230, v[18:21] offset:4096
	v_cndmask_b32_e32 v14, v250, v14, vcc
	v_lshlrev_b32_e32 v223, 2, v14
	ds_bpermute_b32 v14, v223, v1
	ds_bpermute_b32 v15, v223, v5
	v_mov_b32_e32 v18, v3
	s_nop 1
	v_permlane32_swap_b32_e32 v3, v18
	s_waitcnt lgkmcnt(1)
	v_max_f32_e32 v14, v14, v14
	v_max_f32_e32 v1, v1, v14
	s_waitcnt lgkmcnt(0)
	v_max_f32_e32 v14, v15, v15
	v_max_f32_e32 v5, v5, v14
	v_xor_b32_e32 v14, 1, v250
	v_cmp_lt_i32_e32 vcc, v14, v17
	v_add_f32_e32 v3, v3, v18
	v_mov_b32_e32 v21, 0x260
	v_cndmask_b32_e32 v14, v250, v14, vcc
	v_lshlrev_b32_e32 v224, 2, v14
	ds_bpermute_b32 v14, v224, v1
	ds_bpermute_b32 v15, v224, v5
	s_waitcnt lgkmcnt(0)
	s_barrier
	v_max_f32_e32 v14, v14, v14
	v_max_f32_e32 v1, v1, v14
	v_mul_f32_e32 v0, v0, v1
	v_mul_f32_e32 v1, 0x4f800000, v0
	v_cmp_gt_f32_e32 vcc, s52, v0
	v_max_f32_e32 v14, v15, v15
	s_nop 0
	v_cndmask_b32_e32 v1, v0, v1, vcc
	v_sqrt_f32_e32 v15, v1
	v_max_f32_e32 v0, v5, v14
	v_mul_f32_e32 v20, v3, v0
	v_mov_b32_e32 v0, 0
	v_add_u32_e32 v3, -1, v15
	v_fma_f32 v5, -v3, v15, v1
	v_cmp_ge_f32_e64 s[40:41], 0, v5
	v_add_u32_e32 v5, 1, v15
	v_fma_f32 v14, -v5, v15, v1
	v_cndmask_b32_e64 v3, v15, v3, s[40:41]
	v_cmp_lt_f32_e64 s[40:41], 0, v14
	v_mov_b32_e32 v22, v0
	v_mov_b32_e32 v23, v0
	v_cndmask_b32_e64 v3, v3, v5, s[40:41]
	v_mul_f32_e32 v5, 0x37800000, v3
	v_cndmask_b32_e32 v3, v3, v5, vcc
	v_mov_b32_e32 v5, v201
	v_cmp_class_f32_e32 vcc, v1, v21
	v_lshlrev_b64 v[4:5], 1, v[4:5]
	v_lshl_add_u64 v[14:15], s[76:77], 0, v[4:5]
	v_cndmask_b32_e32 v1, v3, v1, vcc
	v_add_u32_e32 v3, 0x2000, v232
	v_lshl_add_u64 v[16:17], v[14:15], 0, s[66:67]
	v_readfirstlane_b32 s8, v3
	v_add_u32_e32 v3, 0x1000, v232
	v_lshl_add_u64 v[18:19], v[14:15], 0, s[26:27]
	global_load_lds_dwordx4 v[16:17], off
	s_mov_b32 m0, s8
	v_readfirstlane_b32 s8, v3
	global_load_lds_dwordx4 v[18:19], off
	v_lshl_add_u64 v[16:17], v[14:15], 0, s[18:19]
	s_mov_b32 m0, s8
	v_add_u32_e32 v3, 0x3000, v232
	global_load_lds_dwordx4 v[16:17], off
	s_mov_b64 s[18:19], 0x2c480
	v_readfirstlane_b32 s8, v3
	v_mov_b32_e32 v3, v201
	v_add_u32_e32 v17, 0x4000, v232
	v_lshl_add_u64 v[14:15], v[14:15], 0, s[18:19]
; __device__ __forceinline__ void attn_item(const P& p, int layer, int item, char* lds) {
;     ...
;     mC1 = sqrtf(qs1 * k1) * 1.4426950408889634f; mC2 = sqrtf(qs2 * k2) * 1.4426950408889634f; }
;   float l1 = 0.f, l2 = 0.f;
;   f32x16 o1[4], o2[4];
; #pragma unroll
;   for (int d = 0; d < 4; ++d) { o1[d] = f32x16{}; o2[d] = f32x16{}; }
;     ...
;   __syncthreads();
;   ISSUE_T(0, 0);
;   for (int j = 0; j < NTILE; ++j) {
;     asm volatile("s_waitcnt vmcnt(0)" ::: "memory"); __syncthreads();
	s_mov_b32 m0, s8
	v_lshl_add_u64 v[2:3], v[2:3], 1, s[76:77]
	s_mov_b64 s[18:19], 0x800
	v_readfirstlane_b32 s8, v17
	v_add_u32_e32 v17, 0x5000, v232
	global_load_lds_dwordx4 v[14:15], off
	v_lshl_add_u64 v[14:15], v[2:3], 0, s[18:19]
	s_mov_b32 m0, s8
	s_mov_b64 s[18:19], 0x16800
	v_readfirstlane_b32 s8, v17
	v_add_u32_e32 v17, 0x6000, v232
	global_load_lds_dwordx4 v[14:15], off
	v_lshl_add_u64 v[14:15], v[2:3], 0, s[18:19]
	s_mov_b32 m0, s8
	s_mov_b64 s[18:19], 0x2c800
	v_readfirstlane_b32 s8, v17
	global_load_lds_dwordx4 v[14:15], off
	v_lshl_add_u64 v[14:15], v[2:3], 0, s[18:19]
	s_mov_b32 m0, s8
	s_mov_b64 s[18:19], 0x42800
	global_load_lds_dwordx4 v[14:15], off
	v_add_u32_e32 v14, 0x7000, v232
	v_lshl_add_u64 v[2:3], v[2:3], 0, s[18:19]
	v_readfirstlane_b32 s8, v14
	s_mov_b32 m0, s8
	v_mul_f32_e32 v14, 0x4f800000, v20
	global_load_lds_dwordx4 v[2:3], off
	v_cmp_gt_f32_e32 vcc, s52, v20
	s_movk_i32 s8, 0x118
	v_bfe_u32 v16, v214, 1, 3
	v_cndmask_b32_e32 v14, v20, v14, vcc
	v_sqrt_f32_e32 v15, v14
	v_mul_f32_e32 v233, 0xbfb8aa3b, v1
	v_lshrrev_b32_e32 v1, 3, v8
	v_mov_b32_e32 v8, v0
	v_add_u32_e32 v2, -1, v15
	v_fma_f32 v3, -v2, v15, v14
	v_cmp_ge_f32_e64 s[40:41], 0, v3
	v_add_u32_e32 v3, 1, v15
	v_mov_b32_e32 v17, v0
	v_cndmask_b32_e64 v2, v15, v2, s[40:41]
	v_fma_f32 v15, -v3, v15, v14
	v_cmp_lt_f32_e64 s[40:41], 0, v15
	v_mov_b32_e32 v15, v0
	v_mov_b32_e32 v18, v0
	v_cndmask_b32_e64 v2, v2, v3, s[40:41]
	v_mul_f32_e32 v3, 0x37800000, v2
	v_cndmask_b32_e32 v2, v2, v3, vcc
	v_and_or_b32 v3, v10, s8, v11
	s_cselect_b32 s8, 0, 0
	s_addk_i32 s8, 0x4000
	v_add3_u32 v234, v13, s8, v3
	v_bitop3_b32 v3, v227, v9, 7 bitop3:0x78
	v_lshlrev_b32_e32 v239, 4, v3
	v_bitop3_b32 v3, v227, v16, 2 bitop3:0x36
	s_movk_i32 s8, 0x5800
	v_cmp_class_f32_e32 vcc, v14, v21
	v_lshlrev_b32_e32 v238, 4, v3
	v_bitop3_b32 v3, v227, v16, 4 bitop3:0x36
	v_mul_lo_u32 v1, v1, s8
	v_cndmask_b32_e32 v2, v2, v14, vcc
	v_lshlrev_b32_e32 v237, 4, v3
	v_bitop3_b32 v3, v227, v16, 6 bitop3:0x36
	v_mad_u32_u24 v1, v6, s33, v1
	s_add_u32 s18, s81, s7
	v_lshlrev_b32_e32 v235, 4, v3
	v_mul_f32_e32 v231, 0xbfb8aa3b, v2
	v_or3_b32 v2, v1, v7, v12
	v_mov_b32_e32 v3, v201
	s_addc_u32 s19, s82, s3
	v_lshl_add_u64 v[206:207], v[2:3], 1, s[18:19]
	v_lshl_add_u64 v[208:209], s[18:19], 0, v[4:5]
	s_mov_b64 s[40:41], 0
	v_mov_b32_e32 v1, v0
	v_mov_b32_e32 v2, v0
	v_mov_b32_e32 v3, v0
	v_mov_b32_e32 v4, v0
	v_mov_b32_e32 v5, v0
	v_mov_b32_e32 v6, v0
	v_mov_b32_e32 v7, v0
	v_mov_b32_e32 v9, v0
	v_mov_b32_e32 v10, v0
	v_mov_b32_e32 v11, v0
	v_mov_b32_e32 v12, v0
	v_mov_b32_e32 v13, v0
	v_mov_b32_e32 v14, v0
	v_mov_b32_e32 v16, v0
	v_mov_b32_e32 v19, v0
	v_mov_b32_e32 v20, v0
	v_mov_b32_e32 v21, v0
	v_mov_b32_e32 v24, v0
	v_mov_b32_e32 v25, v0
	v_mov_b32_e32 v26, v0
	v_mov_b32_e32 v27, v0
	v_mov_b32_e32 v28, v0
	v_mov_b32_e32 v29, v0
	v_mov_b32_e32 v30, v0
	v_mov_b32_e32 v31, v0
	v_mov_b32_e32 v32, v0
	v_mov_b32_e32 v33, v0
	v_mov_b32_e32 v34, v0
	v_mov_b32_e32 v35, v0
	v_mov_b32_e32 v36, v0
	v_mov_b32_e32 v37, v0
	v_mov_b32_e32 v38, v0
	v_mov_b32_e32 v39, v0
	v_mov_b32_e32 v40, v0
	v_mov_b32_e32 v41, v0
	v_mov_b32_e32 v42, v0
	v_mov_b32_e32 v43, v0
	v_mov_b32_e32 v44, v0
	v_mov_b32_e32 v45, v0
	v_mov_b32_e32 v46, v0
	v_mov_b32_e32 v47, v0
	v_mov_b32_e32 v48, v0
	v_mov_b32_e32 v49, v0
	v_mov_b32_e32 v50, v0
	v_mov_b32_e32 v51, v0
	v_mov_b32_e32 v52, v0
	v_mov_b32_e32 v53, v0
	v_mov_b32_e32 v54, v0
	v_mov_b32_e32 v55, v0
	v_mov_b32_e32 v56, v0
	v_mov_b32_e32 v57, v0
	v_mov_b32_e32 v58, v0
	v_mov_b32_e32 v59, v0
	v_mov_b32_e32 v60, v0
	v_mov_b32_e32 v61, v0
	v_mov_b32_e32 v62, v0
	v_mov_b32_e32 v63, v0
	v_mov_b32_e32 v64, v0
	v_mov_b32_e32 v65, v0
	v_mov_b32_e32 v66, v0
	v_mov_b32_e32 v67, v0
	v_mov_b32_e32 v68, v0
	v_mov_b32_e32 v69, v0
	v_mov_b32_e32 v70, v0
	v_mov_b32_e32 v71, v0
	v_mov_b32_e32 v72, v0
	v_mov_b32_e32 v73, v0
	v_mov_b32_e32 v74, v0
	v_mov_b32_e32 v75, v0
	v_mov_b32_e32 v76, v0
	v_mov_b32_e32 v77, v0
	v_mov_b32_e32 v78, v0
	v_mov_b32_e32 v79, v0
	v_mov_b32_e32 v80, v0
	v_mov_b32_e32 v81, v0
	v_mov_b32_e32 v82, v0
	v_mov_b32_e32 v83, v0
	v_mov_b32_e32 v84, v0
	v_mov_b32_e32 v85, v0
	v_mov_b32_e32 v86, v0
	v_mov_b32_e32 v87, v0
	v_mov_b32_e32 v88, v0
	v_mov_b32_e32 v89, v0
	v_mov_b32_e32 v90, v0
	v_mov_b32_e32 v91, v0
	v_mov_b32_e32 v92, v0
	v_mov_b32_e32 v93, v0
	v_mov_b32_e32 v94, v0
	v_mov_b32_e32 v95, v0
	v_mov_b32_e32 v96, v0
	v_mov_b32_e32 v97, v0
	v_mov_b32_e32 v98, v0
	v_mov_b32_e32 v99, v0
	v_mov_b32_e32 v100, v0
	v_mov_b32_e32 v101, v0
	v_mov_b32_e32 v102, v0
	v_mov_b32_e32 v103, v0
	v_mov_b32_e32 v104, v0
	v_mov_b32_e32 v105, v0
	v_mov_b32_e32 v106, v0
	v_mov_b32_e32 v107, v0
	v_mov_b32_e32 v108, v0
	v_mov_b32_e32 v109, v0
	v_mov_b32_e32 v110, v0
	v_mov_b32_e32 v111, v0
	v_mov_b32_e32 v112, v0
	v_mov_b32_e32 v113, v0
	v_mov_b32_e32 v114, v0
	v_mov_b32_e32 v115, v0
	v_mov_b32_e32 v116, v0
	v_mov_b32_e32 v117, v0
	v_mov_b32_e32 v118, v0
	v_mov_b32_e32 v119, v0
	v_mov_b32_e32 v120, v0
	v_mov_b32_e32 v121, v0
	v_mov_b32_e32 v122, v0
	v_mov_b32_e32 v123, v0
	v_mov_b32_e32 v124, v0
	v_mov_b32_e32 v125, v0
	v_mov_b32_e32 v126, v0
	v_mov_b32_e32 v127, v0
	v_mov_b32_e32 v204, v0
	v_mov_b32_e32 v205, v0
	v_add_u32_e32 v239, v236, v239
	v_add_u32_e32 v238, v236, v238
	v_add_u32_e32 v237, v236, v237
	v_add_u32_e32 v235, v236, v235
	v_readfirstlane_b32 s7, v232
	v_readfirstlane_b32 s40, v208
	v_readfirstlane_b32 s41, v209
	v_readfirstlane_b32 s98, v206
	v_readfirstlane_b32 s99, v207
	s_nop 3
	s_sub_u32 s40, s40, 0x1000
	s_subb_u32 s41, s41, 0
	s_sub_u32 s98, s98, 0x1000
	s_subb_u32 s99, s99, 0
	s_nop 1
	v_subrev_u32_e32 v248, s40, v208
	v_subrev_u32_e32 v249, s98, v206
	s_add_u32 s40, s40, 0xa128300
	s_addc_u32 s41, s41, 0
	s_add_u32 s98, s98, 0xa128700
	s_addc_u32 s99, s99, 0
	s_movk_i32 s6, 64
	s_waitcnt lgkmcnt(0)
	s_waitcnt vmcnt(4)
	s_barrier
; #define MFMA(a, b, c) __builtin_amdgcn_mfma_f32_32x32x16_bf16(a, b, c, 0, 0, 0)
; #define PK4N(PV, BASE, OUT) do { u32x4 w_ = {cvtpk(PV[BASE + 0], PV[BASE + 1]), cvtpk(PV[BASE + 2], PV[BASE + 3]), \
;     cvtpk(PV[BASE + 4], PV[BASE + 5]), cvtpk(PV[BASE + 6], PV[BASE + 7])}; OUT = *reinterpret_cast<bf16x8*>(&w_); } while (0)
; __device__ __forceinline__ void att_qkt(f32x16& p0, f32x16& p1, const char* Kb, const bf16x8 (&qr)[4], int koff, int ksw, int hi) {
;   p0 = f32x16{}; p1 = f32x16{};
; #pragma unroll
;   for (int d0 = 0; d0 < 4; ++d0) {
;     const int co = ((d0 * 2 + hi) ^ ksw) << 4;
;     const bf16x8 b0 = *(const bf16x8*)(Kb + koff + co);
;     const bf16x8 b1 = *(const bf16x8*)(Kb + koff + 4096 + co);
;     p0 = MFMA(b0, qr[d0], p0); p1 = MFMA(b1, qr[d0], p1);
;   }
; }
; __device__ __forceinline__ void sm_fixed(f32x16& p0, f32x16& p1, float mC, float& l_reg, bf16x8& pa0, bf16x8& pa1, bf16x8& pa2, bf16x8& pa3) {
;   constexpr float C = 1.4426950408889634f;
; #pragma unroll
;   for (int r = 0; r < 16; ++r) p0[r] = __builtin_amdgcn_exp2f(fmaf(p0[r], C, -mC));
; #pragma unroll
;   for (int r = 0; r < 16; ++r) p1[r] = __builtin_amdgcn_exp2f(fmaf(p1[r], C, -mC));
;   float ps = 0;
; #pragma unroll
;   for (int r = 0; r < 16; ++r) ps += p0[r];
; #pragma unroll
;   for (int r = 0; r < 16; ++r) ps += p1[r];
;   { auto rr = __builtin_amdgcn_permlane32_swap(__float_as_uint(ps), __float_as_uint(ps), false, false);
;     ps = __uint_as_float(rr[0]) + __uint_as_float(rr[1]); }
;   l_reg += ps;
;     ...
;   PK4N(p0, 0, pa0); PK4N(p0, 8, pa1); PK4N(p1, 0, pa2); PK4N(p1, 8, pa3);
;     ...
; }
	ds_read_b128 v[240:243], v239 offset:0
	ds_read_b128 v[244:247], v238 offset:0
	ds_read_b128 v[218:221], v237 offset:0
	ds_read_b128 v[210:213], v235 offset:0
	s_waitcnt lgkmcnt(3)
	v_mfma_f32_32x32x16_bf16 v[128:143], v[240:243], v[180:183], 0
	ds_read_b128 v[240:243], v239 offset:4096
	s_add_u32 m0, s7, 0x8000
	s_nop 0
	global_load_lds_dwordx4 v248, s[40:41]
	s_waitcnt lgkmcnt(3)
	v_mfma_f32_32x32x16_bf16 v[128:143], v[244:247], v[176:179], v[128:143]
	ds_read_b128 v[244:247], v238 offset:4096
	s_add_u32 m0, s7, 0xa000
	s_add_u32 s18, s40, 0x80
	s_addc_u32 s19, s41, 0
	global_load_lds_dwordx4 v248, s[18:19]
	s_waitcnt lgkmcnt(3)
	v_mfma_f32_32x32x16_bf16 v[128:143], v[218:221], v[172:175], v[128:143]
	ds_read_b128 v[218:221], v237 offset:4096
	s_add_u32 m0, s7, 0x9000
	s_add_u32 s18, s40, 0x2c000
	s_addc_u32 s19, s41, 0
	global_load_lds_dwordx4 v248, s[18:19]
	s_waitcnt lgkmcnt(3)
	v_mfma_f32_32x32x16_bf16 v[128:143], v[210:213], v[168:171], v[128:143]
	ds_read_b128 v[210:213], v235 offset:4096
	s_add_u32 m0, s7, 0xb000
	s_add_u32 s18, s40, 0x2c080
	s_addc_u32 s19, s41, 0
	global_load_lds_dwordx4 v248, s[18:19]
	s_add_u32 s40, s40, 0x58000
	s_addc_u32 s41, s41, 0
	s_waitcnt lgkmcnt(3)
	v_mfma_f32_32x32x16_bf16 v[144:159], v[240:243], v[180:183], 0
	ds_read_b128 v[240:243], v239 offset:8192
	s_nop 1
	v_fmamk_f32 v128, v128, 0x3fb8aa3b, v233
	v_fmamk_f32 v129, v129, 0x3fb8aa3b, v233
	v_exp_f32_e32 v128, v128
	v_exp_f32_e32 v129, v129
	v_add_f32_e32 v204, v204, v128
	v_add_f32_e32 v204, v204, v129
	v_cvt_pk_bf16_f32 v184, v128, v129
	v_fmamk_f32 v130, v130, 0x3fb8aa3b, v233
	v_fmamk_f32 v131, v131, 0x3fb8aa3b, v233
	v_exp_f32_e32 v130, v130
	v_exp_f32_e32 v131, v131
	v_add_f32_e32 v204, v204, v130
	v_add_f32_e32 v204, v204, v131
	v_cvt_pk_bf16_f32 v185, v130, v131
	s_waitcnt lgkmcnt(3)
	v_mfma_f32_32x32x16_bf16 v[144:159], v[244:247], v[176:179], v[144:159]
	ds_read_b128 v[244:247], v238 offset:8192
	v_fmamk_f32 v132, v132, 0x3fb8aa3b, v233
	v_fmamk_f32 v133, v133, 0x3fb8aa3b, v233
	v_exp_f32_e32 v132, v132
	v_exp_f32_e32 v133, v133
	v_add_f32_e32 v204, v204, v132
	v_add_f32_e32 v204, v204, v133
	v_cvt_pk_bf16_f32 v186, v132, v133
	v_fmamk_f32 v134, v134, 0x3fb8aa3b, v233
	v_fmamk_f32 v135, v135, 0x3fb8aa3b, v233
	v_exp_f32_e32 v134, v134
	v_exp_f32_e32 v135, v135
	v_add_f32_e32 v204, v204, v134
	v_add_f32_e32 v204, v204, v135
	v_cvt_pk_bf16_f32 v187, v134, v135
	s_waitcnt lgkmcnt(3)
	v_mfma_f32_32x32x16_bf16 v[144:159], v[218:221], v[172:175], v[144:159]
	ds_read_b128 v[218:221], v237 offset:8192
	v_fmamk_f32 v136, v136, 0x3fb8aa3b, v233
	v_fmamk_f32 v137, v137, 0x3fb8aa3b, v233
	v_exp_f32_e32 v136, v136
	v_exp_f32_e32 v137, v137
	v_add_f32_e32 v204, v204, v136
	v_add_f32_e32 v204, v204, v137
	v_cvt_pk_bf16_f32 v188, v136, v137
	v_fmamk_f32 v138, v138, 0x3fb8aa3b, v233
	v_fmamk_f32 v139, v139, 0x3fb8aa3b, v233
	v_exp_f32_e32 v138, v138
	v_exp_f32_e32 v139, v139
	v_add_f32_e32 v204, v204, v138
	v_add_f32_e32 v204, v204, v139
	v_cvt_pk_bf16_f32 v189, v138, v139
	s_waitcnt lgkmcnt(3)
	v_mfma_f32_32x32x16_bf16 v[144:159], v[210:213], v[168:171], v[144:159]
	ds_read_b128 v[210:213], v230 offset:0
	v_fmamk_f32 v140, v140, 0x3fb8aa3b, v233
	v_fmamk_f32 v141, v141, 0x3fb8aa3b, v233
	v_exp_f32_e32 v140, v140
	v_exp_f32_e32 v141, v141
	v_add_f32_e32 v204, v204, v140
	v_add_f32_e32 v204, v204, v141
	v_cvt_pk_bf16_f32 v190, v140, v141
	v_fmamk_f32 v142, v142, 0x3fb8aa3b, v233
	v_fmamk_f32 v143, v143, 0x3fb8aa3b, v233
	v_exp_f32_e32 v142, v142
	v_exp_f32_e32 v143, v143
	v_add_f32_e32 v204, v204, v142
	v_add_f32_e32 v204, v204, v143
	v_cvt_pk_bf16_f32 v191, v142, v143
.Lattn_loop:
	s_waitcnt vmcnt(4)
	s_barrier
	s_waitcnt lgkmcnt(3)
	v_mfma_f32_32x32x16_bf16 v[128:143], v[240:243], v[164:167], 0
	ds_read_b128 v[240:243], v235 offset:8192
	v_fmamk_f32 v144, v144, 0x3fb8aa3b, v233
	v_fmamk_f32 v145, v145, 0x3fb8aa3b, v233
	v_exp_f32_e32 v144, v144
	v_exp_f32_e32 v145, v145
	v_add_f32_e32 v204, v204, v144
	s_add_u32 m0, s7, 0xc000
	s_nop 0
	global_load_lds_dwordx4 v249, s[98:99]
	s_waitcnt lgkmcnt(3)
	v_mfma_f32_32x32x16_bf16 v[128:143], v[244:247], v[160:163], v[128:143]
	ds_read_b128 v[244:247], v230 offset:4096
	v_add_f32_e32 v204, v204, v145
	v_cvt_pk_bf16_f32 v192, v144, v145
	v_fmamk_f32 v146, v146, 0x3fb8aa3b, v233
	v_fmamk_f32 v147, v147, 0x3fb8aa3b, v233
	v_exp_f32_e32 v146, v146
	s_add_u32 m0, s7, 0xd000
	s_add_u32 s18, s98, 0x16000
	s_addc_u32 s19, s99, 0
	global_load_lds_dwordx4 v249, s[18:19]
	s_waitcnt lgkmcnt(2)
	v_mfma_f32_32x32x16_bf16 v[128:143], v[218:221], v[210:213], v[128:143]
	ds_read_b64_tr_b16 v[218:219], v234 offset:0
	ds_read_b64_tr_b16 v[220:221], v234 offset:2048
	ds_read_b64_tr_b16 v[210:211], v234 offset:512
	ds_read_b64_tr_b16 v[212:213], v234 offset:2560
	v_exp_f32_e32 v147, v147
	v_add_f32_e32 v204, v204, v146
	v_add_f32_e32 v204, v204, v147
	v_cvt_pk_bf16_f32 v193, v146, v147
	v_fmamk_f32 v148, v148, 0x3fb8aa3b, v233
	s_add_u32 m0, s7, 0xe000
	s_add_u32 s18, s98, 0x2c000
	s_addc_u32 s19, s99, 0
	global_load_lds_dwordx4 v249, s[18:19]
	s_waitcnt lgkmcnt(4)
	v_mfma_f32_32x32x16_bf16 v[128:143], v[240:243], v[244:247], v[128:143]
	ds_read_b64_tr_b16 v[240:241], v234 offset:1024
	ds_read_b64_tr_b16 v[242:243], v234 offset:3072
	ds_read_b64_tr_b16 v[244:245], v234 offset:1536
	ds_read_b64_tr_b16 v[246:247], v234 offset:3584
	v_fmamk_f32 v149, v149, 0x3fb8aa3b, v233
	v_exp_f32_e32 v148, v148
	v_exp_f32_e32 v149, v149
	v_add_f32_e32 v204, v204, v148
	v_add_f32_e32 v204, v204, v149
	s_add_u32 m0, s7, 0xf000
	s_add_u32 s18, s98, 0x42000
	s_addc_u32 s19, s99, 0
	global_load_lds_dwordx4 v249, s[18:19]
	s_add_u32 s98, s98, 0x58000
	s_addc_u32 s99, s99, 0
	s_waitcnt lgkmcnt(6)
; #define SBAR() __builtin_amdgcn_sched_barrier(0)
; #define MFMA(a, b, c) __builtin_amdgcn_mfma_f32_32x32x16_bf16(a, b, c, 0, 0, 0)
; #define PK4N(PV, BASE, OUT) do { u32x4 w_ = {cvtpk(PV[BASE + 0], PV[BASE + 1]), cvtpk(PV[BASE + 2], PV[BASE + 3]), \
;     cvtpk(PV[BASE + 4], PV[BASE + 5]), cvtpk(PV[BASE + 6], PV[BASE + 7])}; OUT = *reinterpret_cast<bf16x8*>(&w_); } while (0)
; template <int D0> __device__ __forceinline__ void pv_two(f32x16& oa, f32x16& ob, int vb, bf16x8 a0, bf16x8 a1, bf16x8 a2, bf16x8 a3,
;                                                          bf16x8 b0, bf16x8 b1, bf16x8 b2, bf16x8 b3) {
;     ...
;   { const s16x4 l0 = tr_read<v_rd_off(D0, 0, 0)>(vb), h0 = tr_read<v_rd_off(D0, 0, 1)>(vb), l1 = tr_read<v_rd_off(D0, 1, 0)>(vb), h1 = tr_read<v_rd_off(D0, 1, 1)>(vb);
;     asm volatile("s_waitcnt lgkmcnt(0)" ::: "memory"); SBAR();
;     const bf16x8 v0 = PKV(l0, h0), v1 = PKV(l1, h1);
;     oa = MFMA(a0, v0, oa); ob = MFMA(b0, v0, ob); oa = MFMA(a1, v1, oa); ob = MFMA(b1, v1, ob); }
;   { const s16x4 l2 = tr_read<v_rd_off(D0, 2, 0)>(vb), h2 = tr_read<v_rd_off(D0, 2, 1)>(vb), l3 = tr_read<v_rd_off(D0, 3, 0)>(vb), h3 = tr_read<v_rd_off(D0, 3, 1)>(vb);
;     asm volatile("s_waitcnt lgkmcnt(0)" ::: "memory"); SBAR();
;     const bf16x8 v2 = PKV(l2, h2), v3 = PKV(l3, h3);
;     oa = MFMA(a2, v2, oa); ob = MFMA(b2, v2, ob); oa = MFMA(a3, v3, oa); ob = MFMA(b3, v3, ob); }
;     ...
; }
; __device__ __forceinline__ void sm_fixed(f32x16& p0, f32x16& p1, float mC, float& l_reg, bf16x8& pa0, bf16x8& pa1, bf16x8& pa2, bf16x8& pa3) {
;   constexpr float C = 1.4426950408889634f;
; #pragma unroll
;   for (int r = 0; r < 16; ++r) p0[r] = __builtin_amdgcn_exp2f(fmaf(p0[r], C, -mC));
; #pragma unroll
;   for (int r = 0; r < 16; ++r) p1[r] = __builtin_amdgcn_exp2f(fmaf(p1[r], C, -mC));
;   float ps = 0;
; #pragma unroll
;   for (int r = 0; r < 16; ++r) ps += p0[r];
; #pragma unroll
;   for (int r = 0; r < 16; ++r) ps += p1[r];
;   { auto rr = __builtin_amdgcn_permlane32_swap(__float_as_uint(ps), __float_as_uint(ps), false, false);
;     ps = __uint_as_float(rr[0]) + __uint_as_float(rr[1]); }
;   l_reg += ps;
;     ...
;   PK4N(p0, 0, pa0); PK4N(p0, 8, pa1); PK4N(p1, 0, pa2); PK4N(p1, 8, pa3);
;     ...
; }
	v_mfma_f32_32x32x16_bf16 v[64:79], v[184:187], v[218:221], v[64:79]
	ds_read_b64_tr_b16 v[218:219], v234 offset:4096
	ds_read_b64_tr_b16 v[220:221], v234 offset:6144
	v_cvt_pk_bf16_f32 v194, v148, v149
	v_fmamk_f32 v150, v150, 0x3fb8aa3b, v233
	v_fmamk_f32 v151, v151, 0x3fb8aa3b, v233
	v_exp_f32_e32 v150, v150
	v_exp_f32_e32 v151, v151
	s_waitcnt lgkmcnt(6)
	v_mfma_f32_32x32x16_bf16 v[80:95], v[184:187], v[210:213], v[80:95]
	ds_read_b64_tr_b16 v[210:211], v234 offset:4608
	ds_read_b64_tr_b16 v[212:213], v234 offset:6656
	v_add_f32_e32 v204, v204, v150
	v_add_f32_e32 v204, v204, v151
	v_cvt_pk_bf16_f32 v195, v150, v151
	v_fmamk_f32 v152, v152, 0x3fb8aa3b, v233
	v_fmamk_f32 v153, v153, 0x3fb8aa3b, v233
	s_waitcnt lgkmcnt(6)
	v_mfma_f32_32x32x16_bf16 v[96:111], v[184:187], v[240:243], v[96:111]
	ds_read_b64_tr_b16 v[240:241], v234 offset:5120
	ds_read_b64_tr_b16 v[242:243], v234 offset:7168
	v_exp_f32_e32 v152, v152
	v_exp_f32_e32 v153, v153
	v_add_f32_e32 v204, v204, v152
	v_add_f32_e32 v204, v204, v153
	v_cvt_pk_bf16_f32 v196, v152, v153
	s_waitcnt lgkmcnt(6)
	v_mfma_f32_32x32x16_bf16 v[112:127], v[184:187], v[244:247], v[112:127]
	ds_read_b64_tr_b16 v[244:245], v234 offset:5632
	ds_read_b64_tr_b16 v[246:247], v234 offset:7680
	v_fmamk_f32 v154, v154, 0x3fb8aa3b, v233
	v_fmamk_f32 v155, v155, 0x3fb8aa3b, v233
	v_exp_f32_e32 v154, v154
	v_exp_f32_e32 v155, v155
	v_add_f32_e32 v204, v204, v154
	s_waitcnt lgkmcnt(6)
	v_mfma_f32_32x32x16_bf16 v[64:79], v[188:191], v[218:221], v[64:79]
	ds_read_b64_tr_b16 v[218:219], v234 offset:8192
	ds_read_b64_tr_b16 v[220:221], v234 offset:10240
	v_add_f32_e32 v204, v204, v155
	v_cvt_pk_bf16_f32 v197, v154, v155
	v_fmamk_f32 v156, v156, 0x3fb8aa3b, v233
	v_fmamk_f32 v157, v157, 0x3fb8aa3b, v233
	s_waitcnt lgkmcnt(6)
	v_mfma_f32_32x32x16_bf16 v[80:95], v[188:191], v[210:213], v[80:95]
	ds_read_b64_tr_b16 v[210:211], v234 offset:8704
	ds_read_b64_tr_b16 v[212:213], v234 offset:10752
	v_exp_f32_e32 v156, v156
	v_exp_f32_e32 v157, v157
	v_add_f32_e32 v204, v204, v156
	v_add_f32_e32 v204, v204, v157
	s_waitcnt lgkmcnt(6)
	v_mfma_f32_32x32x16_bf16 v[96:111], v[188:191], v[240:243], v[96:111]
	ds_read_b64_tr_b16 v[240:241], v234 offset:9216
	ds_read_b64_tr_b16 v[242:243], v234 offset:11264
	v_cvt_pk_bf16_f32 v198, v156, v157
	v_fmamk_f32 v158, v158, 0x3fb8aa3b, v233
	v_fmamk_f32 v159, v159, 0x3fb8aa3b, v233
	v_exp_f32_e32 v158, v158
	s_waitcnt lgkmcnt(6)
	v_mfma_f32_32x32x16_bf16 v[112:127], v[188:191], v[244:247], v[112:127]
	ds_read_b64_tr_b16 v[244:245], v234 offset:9728
	ds_read_b64_tr_b16 v[246:247], v234 offset:11776
	v_exp_f32_e32 v159, v159
	v_add_f32_e32 v204, v204, v158
	v_add_f32_e32 v204, v204, v159
	v_cvt_pk_bf16_f32 v199, v158, v159
	s_waitcnt lgkmcnt(6)
	v_mfma_f32_32x32x16_bf16 v[64:79], v[192:195], v[218:221], v[64:79]
	ds_read_b128 v[218:221], v239 offset:12288
	v_fmamk_f32 v128, v128, 0x3fb8aa3b, v231
	v_fmamk_f32 v129, v129, 0x3fb8aa3b, v231
	v_exp_f32_e32 v128, v128
	v_exp_f32_e32 v129, v129
	v_add_f32_e32 v205, v205, v128
	s_waitcnt lgkmcnt(5)
	v_mfma_f32_32x32x16_bf16 v[80:95], v[192:195], v[210:213], v[80:95]
	ds_read_b128 v[210:213], v238 offset:12288
	v_add_f32_e32 v205, v205, v129
	v_cvt_pk_bf16_f32 v184, v128, v129
	v_fmamk_f32 v130, v130, 0x3fb8aa3b, v231
	v_fmamk_f32 v131, v131, 0x3fb8aa3b, v231
	v_exp_f32_e32 v130, v130
	s_waitcnt lgkmcnt(4)
	v_mfma_f32_32x32x16_bf16 v[96:111], v[192:195], v[240:243], v[96:111]
	ds_read_b128 v[240:243], v237 offset:12288
	v_exp_f32_e32 v131, v131
	v_add_f32_e32 v205, v205, v130
	v_add_f32_e32 v205, v205, v131
	v_cvt_pk_bf16_f32 v185, v130, v131
	v_fmamk_f32 v132, v132, 0x3fb8aa3b, v231
	s_waitcnt lgkmcnt(3)
	v_mfma_f32_32x32x16_bf16 v[112:127], v[192:195], v[244:247], v[112:127]
	ds_read_b128 v[244:247], v230 offset:0
	v_fmamk_f32 v133, v133, 0x3fb8aa3b, v231
	v_exp_f32_e32 v132, v132
	v_exp_f32_e32 v133, v133
	v_add_f32_e32 v205, v205, v132
	v_add_f32_e32 v205, v205, v133
	s_waitcnt lgkmcnt(3)
	v_mfma_f32_32x32x16_bf16 v[144:159], v[218:221], v[164:167], 0
	ds_read_b128 v[218:221], v235 offset:12288
	v_cvt_pk_bf16_f32 v186, v132, v133
	v_fmamk_f32 v134, v134, 0x3fb8aa3b, v231
	v_fmamk_f32 v135, v135, 0x3fb8aa3b, v231
	v_exp_f32_e32 v134, v134
	v_exp_f32_e32 v135, v135
	s_waitcnt lgkmcnt(3)
	v_mfma_f32_32x32x16_bf16 v[144:159], v[210:213], v[160:163], v[144:159]
	ds_read_b128 v[210:213], v230 offset:4096
	v_add_f32_e32 v205, v205, v134
	v_add_f32_e32 v205, v205, v135
	v_cvt_pk_bf16_f32 v187, v134, v135
	v_fmamk_f32 v136, v136, 0x3fb8aa3b, v231
	v_fmamk_f32 v137, v137, 0x3fb8aa3b, v231
	s_waitcnt lgkmcnt(2)
	v_mfma_f32_32x32x16_bf16 v[144:159], v[240:243], v[244:247], v[144:159]
	ds_read_b64_tr_b16 v[240:241], v234 offset:12288
	ds_read_b64_tr_b16 v[242:243], v234 offset:14336
	ds_read_b64_tr_b16 v[244:245], v234 offset:12800
	ds_read_b64_tr_b16 v[246:247], v234 offset:14848
	v_exp_f32_e32 v136, v136
	v_exp_f32_e32 v137, v137
	v_add_f32_e32 v205, v205, v136
	v_add_f32_e32 v205, v205, v137
	v_cvt_pk_bf16_f32 v188, v136, v137
	s_waitcnt lgkmcnt(4)
	v_mfma_f32_32x32x16_bf16 v[144:159], v[218:221], v[210:213], v[144:159]
	ds_read_b64_tr_b16 v[218:219], v234 offset:13312
	ds_read_b64_tr_b16 v[220:221], v234 offset:15360
	ds_read_b64_tr_b16 v[210:211], v234 offset:13824
	ds_read_b64_tr_b16 v[212:213], v234 offset:15872
	v_fmamk_f32 v138, v138, 0x3fb8aa3b, v231
	v_fmamk_f32 v139, v139, 0x3fb8aa3b, v231
	v_exp_f32_e32 v138, v138
	v_exp_f32_e32 v139, v139
	v_add_f32_e32 v205, v205, v138
	s_waitcnt lgkmcnt(6)
	v_mfma_f32_32x32x16_bf16 v[64:79], v[196:199], v[240:243], v[64:79]
	ds_read_b64_tr_b16 v[240:241], v234 offset:0
	ds_read_b64_tr_b16 v[242:243], v234 offset:2048
	v_add_f32_e32 v205, v205, v139
	v_cvt_pk_bf16_f32 v189, v138, v139
	v_fmamk_f32 v140, v140, 0x3fb8aa3b, v231
	v_fmamk_f32 v141, v141, 0x3fb8aa3b, v231
	s_waitcnt lgkmcnt(6)
	v_mfma_f32_32x32x16_bf16 v[80:95], v[196:199], v[244:247], v[80:95]
	ds_read_b64_tr_b16 v[244:245], v234 offset:512
	ds_read_b64_tr_b16 v[246:247], v234 offset:2560
	v_exp_f32_e32 v140, v140
	v_exp_f32_e32 v141, v141
	v_add_f32_e32 v205, v205, v140
	v_add_f32_e32 v205, v205, v141
	s_waitcnt lgkmcnt(6)
	v_mfma_f32_32x32x16_bf16 v[96:111], v[196:199], v[218:221], v[96:111]
	ds_read_b64_tr_b16 v[218:219], v234 offset:1024
	ds_read_b64_tr_b16 v[220:221], v234 offset:3072
	v_cvt_pk_bf16_f32 v190, v140, v141
	v_fmamk_f32 v142, v142, 0x3fb8aa3b, v231
	v_fmamk_f32 v143, v143, 0x3fb8aa3b, v231
	v_exp_f32_e32 v142, v142
	s_waitcnt lgkmcnt(6)
	v_mfma_f32_32x32x16_bf16 v[112:127], v[196:199], v[210:213], v[112:127]
	ds_read_b64_tr_b16 v[210:211], v234 offset:1536
	ds_read_b64_tr_b16 v[212:213], v234 offset:3584
	v_exp_f32_e32 v143, v143
	v_add_f32_e32 v205, v205, v142
	v_add_f32_e32 v205, v205, v143
	v_cvt_pk_bf16_f32 v191, v142, v143
	s_add_i32 s6, s6, -1
	s_cmp_eq_u32 s6, 0
	s_cbranch_scc1 .Lattn_exit
; #define SBAR() __builtin_amdgcn_sched_barrier(0)
; template <int D0> __device__ __forceinline__ void pv_two(f32x16& oa, f32x16& ob, int vb, bf16x8 a0, bf16x8 a1, bf16x8 a2, bf16x8 a3,
;                                                          bf16x8 b0, bf16x8 b1, bf16x8 b2, bf16x8 b3) {
;     ...
;   { const s16x4 l0 = tr_read<v_rd_off(D0, 0, 0)>(vb), h0 = tr_read<v_rd_off(D0, 0, 1)>(vb), l1 = tr_read<v_rd_off(D0, 1, 0)>(vb), h1 = tr_read<v_rd_off(D0, 1, 1)>(vb);
;     asm volatile("s_waitcnt lgkmcnt(0)" ::: "memory"); SBAR();
;     const bf16x8 v0 = PKV(l0, h0), v1 = PKV(l1, h1);
;     oa = MFMA(a0, v0, oa); ob = MFMA(b0, v0, ob); oa = MFMA(a1, v1, oa); ob = MFMA(b1, v1, ob); }
;   { const s16x4 l2 = tr_read<v_rd_off(D0, 2, 0)>(vb), h2 = tr_read<v_rd_off(D0, 2, 1)>(vb), l3 = tr_read<v_rd_off(D0, 3, 0)>(vb), h3 = tr_read<v_rd_off(D0, 3, 1)>(vb);
;     asm volatile("s_waitcnt lgkmcnt(0)" ::: "memory"); SBAR();
;     const bf16x8 v2 = PKV(l2, h2), v3 = PKV(l3, h3);
;     oa = MFMA(a2, v2, oa); ob = MFMA(b2, v2, ob); oa = MFMA(a3, v3, oa); ob = MFMA(b3, v3, ob); }
;     ...
; }
; __device__ __forceinline__ void att_qkt(f32x16& p0, f32x16& p1, const char* Kb, const bf16x8 (&qr)[4], int koff, int ksw, int hi) {
;   p0 = f32x16{}; p1 = f32x16{};
; #pragma unroll
;   for (int d0 = 0; d0 < 4; ++d0) {
;     const int co = ((d0 * 2 + hi) ^ ksw) << 4;
;     const bf16x8 b0 = *(const bf16x8*)(Kb + koff + co);
;     const bf16x8 b1 = *(const bf16x8*)(Kb + koff + 4096 + co);
;     p0 = MFMA(b0, qr[d0], p0); p1 = MFMA(b1, qr[d0], p1);
;   }
; }
; __device__ __forceinline__ void sm_fixed(f32x16& p0, f32x16& p1, float mC, float& l_reg, bf16x8& pa0, bf16x8& pa1, bf16x8& pa2, bf16x8& pa3) {
;   constexpr float C = 1.4426950408889634f;
; #pragma unroll
;   for (int r = 0; r < 16; ++r) p0[r] = __builtin_amdgcn_exp2f(fmaf(p0[r], C, -mC));
; #pragma unroll
;   for (int r = 0; r < 16; ++r) p1[r] = __builtin_amdgcn_exp2f(fmaf(p1[r], C, -mC));
;   float ps = 0;
; #pragma unroll
;   for (int r = 0; r < 16; ++r) ps += p0[r];
; #pragma unroll
;   for (int r = 0; r < 16; ++r) ps += p1[r];
;   { auto rr = __builtin_amdgcn_permlane32_swap(__float_as_uint(ps), __float_as_uint(ps), false, false);
;     ps = __uint_as_float(rr[0]) + __uint_as_float(rr[1]); }
;   l_reg += ps;
;     ...
;   PK4N(p0, 0, pa0); PK4N(p0, 8, pa1); PK4N(p1, 0, pa2); PK4N(p1, 8, pa3);
;     ...
; }
	s_waitcnt vmcnt(4)
	s_barrier
	s_waitcnt lgkmcnt(6)
	v_mfma_f32_32x32x16_bf16 v[0:15], v[184:187], v[240:243], v[0:15]
	ds_read_b128 v[240:243], v239 offset:32768
	v_fmamk_f32 v144, v144, 0x3fb8aa3b, v231
	v_fmamk_f32 v145, v145, 0x3fb8aa3b, v231
	v_exp_f32_e32 v144, v144
	v_exp_f32_e32 v145, v145
	v_add_f32_e32 v205, v205, v144
	s_add_u32 m0, s7, 0x0
	s_nop 0
	global_load_lds_dwordx4 v248, s[40:41]
	s_waitcnt lgkmcnt(5)
	v_mfma_f32_32x32x16_bf16 v[16:31], v[184:187], v[244:247], v[16:31]
	ds_read_b128 v[244:247], v238 offset:32768
	v_add_f32_e32 v205, v205, v145
	v_cvt_pk_bf16_f32 v192, v144, v145
	v_fmamk_f32 v146, v146, 0x3fb8aa3b, v231
	v_fmamk_f32 v147, v147, 0x3fb8aa3b, v231
	v_exp_f32_e32 v146, v146
	s_add_u32 m0, s7, 0x2000
	s_add_u32 s18, s40, 0x80
	s_addc_u32 s19, s41, 0
	global_load_lds_dwordx4 v248, s[18:19]
	s_waitcnt lgkmcnt(4)
	v_mfma_f32_32x32x16_bf16 v[32:47], v[184:187], v[218:221], v[32:47]
	ds_read_b128 v[218:221], v237 offset:32768
	v_exp_f32_e32 v147, v147
	v_add_f32_e32 v205, v205, v146
	v_add_f32_e32 v205, v205, v147
	v_cvt_pk_bf16_f32 v193, v146, v147
	v_fmamk_f32 v148, v148, 0x3fb8aa3b, v231
	s_add_u32 m0, s7, 0x1000
	s_add_u32 s18, s40, 0x2c000
	s_addc_u32 s19, s41, 0
	global_load_lds_dwordx4 v248, s[18:19]
	s_waitcnt lgkmcnt(3)
	v_mfma_f32_32x32x16_bf16 v[48:63], v[184:187], v[210:213], v[48:63]
	ds_read_b128 v[210:213], v235 offset:32768
	v_fmamk_f32 v149, v149, 0x3fb8aa3b, v231
	v_exp_f32_e32 v148, v148
	v_exp_f32_e32 v149, v149
	v_add_f32_e32 v205, v205, v148
	v_add_f32_e32 v205, v205, v149
	s_add_u32 m0, s7, 0x3000
	s_add_u32 s18, s40, 0x2c080
	s_addc_u32 s19, s41, 0
	global_load_lds_dwordx4 v248, s[18:19]
	s_add_u32 s40, s40, 0x58000
	s_addc_u32 s41, s41, 0
	s_waitcnt lgkmcnt(3)
	v_mfma_f32_32x32x16_bf16 v[128:143], v[240:243], v[180:183], 0
	ds_read_b64_tr_b16 v[240:241], v234 offset:4096
	ds_read_b64_tr_b16 v[242:243], v234 offset:6144
	v_cvt_pk_bf16_f32 v194, v148, v149
	v_fmamk_f32 v150, v150, 0x3fb8aa3b, v231
	v_fmamk_f32 v151, v151, 0x3fb8aa3b, v231
	v_exp_f32_e32 v150, v150
	v_exp_f32_e32 v151, v151
	s_waitcnt lgkmcnt(4)
	v_mfma_f32_32x32x16_bf16 v[128:143], v[244:247], v[176:179], v[128:143]
	ds_read_b64_tr_b16 v[244:245], v234 offset:4608
	ds_read_b64_tr_b16 v[246:247], v234 offset:6656
	v_add_f32_e32 v205, v205, v150
	v_add_f32_e32 v205, v205, v151
	v_cvt_pk_bf16_f32 v195, v150, v151
	v_fmamk_f32 v152, v152, 0x3fb8aa3b, v231
	v_fmamk_f32 v153, v153, 0x3fb8aa3b, v231
	s_waitcnt lgkmcnt(5)
	v_mfma_f32_32x32x16_bf16 v[128:143], v[218:221], v[172:175], v[128:143]
	ds_read_b64_tr_b16 v[218:219], v234 offset:5120
	ds_read_b64_tr_b16 v[220:221], v234 offset:7168
	v_exp_f32_e32 v152, v152
	v_exp_f32_e32 v153, v153
	v_add_f32_e32 v205, v205, v152
	v_add_f32_e32 v205, v205, v153
	v_cvt_pk_bf16_f32 v196, v152, v153
	s_waitcnt lgkmcnt(6)
	v_mfma_f32_32x32x16_bf16 v[128:143], v[210:213], v[168:171], v[128:143]
	ds_read_b64_tr_b16 v[210:211], v234 offset:5632
	ds_read_b64_tr_b16 v[212:213], v234 offset:7680
	v_fmamk_f32 v154, v154, 0x3fb8aa3b, v231
	v_fmamk_f32 v155, v155, 0x3fb8aa3b, v231
	v_exp_f32_e32 v154, v154
	v_exp_f32_e32 v155, v155
	v_add_f32_e32 v205, v205, v154
	s_waitcnt lgkmcnt(6)
	v_mfma_f32_32x32x16_bf16 v[0:15], v[188:191], v[240:243], v[0:15]
	ds_read_b64_tr_b16 v[240:241], v234 offset:8192
	ds_read_b64_tr_b16 v[242:243], v234 offset:10240
	v_add_f32_e32 v205, v205, v155
	v_cvt_pk_bf16_f32 v197, v154, v155
	v_fmamk_f32 v156, v156, 0x3fb8aa3b, v231
	v_fmamk_f32 v157, v157, 0x3fb8aa3b, v231
	s_waitcnt lgkmcnt(6)
	v_mfma_f32_32x32x16_bf16 v[16:31], v[188:191], v[244:247], v[16:31]
	ds_read_b64_tr_b16 v[244:245], v234 offset:8704
	ds_read_b64_tr_b16 v[246:247], v234 offset:10752
	v_exp_f32_e32 v156, v156
	v_exp_f32_e32 v157, v157
	v_add_f32_e32 v205, v205, v156
	v_add_f32_e32 v205, v205, v157
	s_waitcnt lgkmcnt(6)
	v_mfma_f32_32x32x16_bf16 v[32:47], v[188:191], v[218:221], v[32:47]
	ds_read_b64_tr_b16 v[218:219], v234 offset:9216
	ds_read_b64_tr_b16 v[220:221], v234 offset:11264
	v_cvt_pk_bf16_f32 v198, v156, v157
	v_fmamk_f32 v158, v158, 0x3fb8aa3b, v231
	v_fmamk_f32 v159, v159, 0x3fb8aa3b, v231
	v_exp_f32_e32 v158, v158
	s_waitcnt lgkmcnt(6)
	v_mfma_f32_32x32x16_bf16 v[48:63], v[188:191], v[210:213], v[48:63]
	ds_read_b64_tr_b16 v[210:211], v234 offset:9728
	ds_read_b64_tr_b16 v[212:213], v234 offset:11776
	v_exp_f32_e32 v159, v159
	v_add_f32_e32 v205, v205, v158
	v_add_f32_e32 v205, v205, v159
	v_cvt_pk_bf16_f32 v199, v158, v159
	s_waitcnt lgkmcnt(6)
	v_mfma_f32_32x32x16_bf16 v[0:15], v[192:195], v[240:243], v[0:15]
	ds_read_b128 v[240:243], v239 offset:36864
	v_fmamk_f32 v128, v128, 0x3fb8aa3b, v233
	v_fmamk_f32 v129, v129, 0x3fb8aa3b, v233
	v_exp_f32_e32 v128, v128
	v_exp_f32_e32 v129, v129
	v_add_f32_e32 v204, v204, v128
	s_waitcnt lgkmcnt(5)
	v_mfma_f32_32x32x16_bf16 v[16:31], v[192:195], v[244:247], v[16:31]
	ds_read_b128 v[244:247], v238 offset:36864
	v_add_f32_e32 v204, v204, v129
	v_cvt_pk_bf16_f32 v184, v128, v129
	v_fmamk_f32 v130, v130, 0x3fb8aa3b, v233
	v_fmamk_f32 v131, v131, 0x3fb8aa3b, v233
	v_exp_f32_e32 v130, v130
	s_waitcnt lgkmcnt(4)
	v_mfma_f32_32x32x16_bf16 v[32:47], v[192:195], v[218:221], v[32:47]
	ds_read_b128 v[218:221], v237 offset:36864
	v_exp_f32_e32 v131, v131
	v_add_f32_e32 v204, v204, v130
	v_add_f32_e32 v204, v204, v131
	v_cvt_pk_bf16_f32 v185, v130, v131
	v_fmamk_f32 v132, v132, 0x3fb8aa3b, v233
	s_waitcnt lgkmcnt(3)
	v_mfma_f32_32x32x16_bf16 v[48:63], v[192:195], v[210:213], v[48:63]
	ds_read_b128 v[210:213], v235 offset:36864
	v_fmamk_f32 v133, v133, 0x3fb8aa3b, v233
	v_exp_f32_e32 v132, v132
	v_exp_f32_e32 v133, v133
	v_add_f32_e32 v204, v204, v132
	v_add_f32_e32 v204, v204, v133
	s_waitcnt lgkmcnt(3)
; #define SBAR() __builtin_amdgcn_sched_barrier(0)
; template <int D0> __device__ __forceinline__ void pv_two(f32x16& oa, f32x16& ob, int vb, bf16x8 a0, bf16x8 a1, bf16x8 a2, bf16x8 a3,
;                                                          bf16x8 b0, bf16x8 b1, bf16x8 b2, bf16x8 b3) {
;     ...
;   { const s16x4 l0 = tr_read<v_rd_off(D0, 0, 0)>(vb), h0 = tr_read<v_rd_off(D0, 0, 1)>(vb), l1 = tr_read<v_rd_off(D0, 1, 0)>(vb), h1 = tr_read<v_rd_off(D0, 1, 1)>(vb);
;     asm volatile("s_waitcnt lgkmcnt(0)" ::: "memory"); SBAR();
;     const bf16x8 v0 = PKV(l0, h0), v1 = PKV(l1, h1);
;     oa = MFMA(a0, v0, oa); ob = MFMA(b0, v0, ob); oa = MFMA(a1, v1, oa); ob = MFMA(b1, v1, ob); }
;   { const s16x4 l2 = tr_read<v_rd_off(D0, 2, 0)>(vb), h2 = tr_read<v_rd_off(D0, 2, 1)>(vb), l3 = tr_read<v_rd_off(D0, 3, 0)>(vb), h3 = tr_read<v_rd_off(D0, 3, 1)>(vb);
;     asm volatile("s_waitcnt lgkmcnt(0)" ::: "memory"); SBAR();
;     const bf16x8 v2 = PKV(l2, h2), v3 = PKV(l3, h3);
;     oa = MFMA(a2, v2, oa); ob = MFMA(b2, v2, ob); oa = MFMA(a3, v3, oa); ob = MFMA(b3, v3, ob); }
;     ...
; }
; __device__ __forceinline__ void att_qkt(f32x16& p0, f32x16& p1, const char* Kb, const bf16x8 (&qr)[4], int koff, int ksw, int hi) {
;   p0 = f32x16{}; p1 = f32x16{};
; #pragma unroll
;   for (int d0 = 0; d0 < 4; ++d0) {
;     const int co = ((d0 * 2 + hi) ^ ksw) << 4;
;     const bf16x8 b0 = *(const bf16x8*)(Kb + koff + co);
;     const bf16x8 b1 = *(const bf16x8*)(Kb + koff + 4096 + co);
;     p0 = MFMA(b0, qr[d0], p0); p1 = MFMA(b1, qr[d0], p1);
;   }
; }
; __device__ __forceinline__ void sm_fixed(f32x16& p0, f32x16& p1, float mC, float& l_reg, bf16x8& pa0, bf16x8& pa1, bf16x8& pa2, bf16x8& pa3) {
;   constexpr float C = 1.4426950408889634f;
; #pragma unroll
;   for (int r = 0; r < 16; ++r) p0[r] = __builtin_amdgcn_exp2f(fmaf(p0[r], C, -mC));
; #pragma unroll
;   for (int r = 0; r < 16; ++r) p1[r] = __builtin_amdgcn_exp2f(fmaf(p1[r], C, -mC));
;   float ps = 0;
; #pragma unroll
;   for (int r = 0; r < 16; ++r) ps += p0[r];
; #pragma unroll
;   for (int r = 0; r < 16; ++r) ps += p1[r];
;   { auto rr = __builtin_amdgcn_permlane32_swap(__float_as_uint(ps), __float_as_uint(ps), false, false);
;     ps = __uint_as_float(rr[0]) + __uint_as_float(rr[1]); }
;   l_reg += ps;
;     ...
;   PK4N(p0, 0, pa0); PK4N(p0, 8, pa1); PK4N(p1, 0, pa2); PK4N(p1, 8, pa3);
;     ...
; }
; #pragma unroll
	v_mfma_f32_32x32x16_bf16 v[144:159], v[240:243], v[180:183], 0
	ds_read_b64_tr_b16 v[240:241], v234 offset:12288
	ds_read_b64_tr_b16 v[242:243], v234 offset:14336
	v_cvt_pk_bf16_f32 v186, v132, v133
	v_fmamk_f32 v134, v134, 0x3fb8aa3b, v233
	v_fmamk_f32 v135, v135, 0x3fb8aa3b, v233
	v_exp_f32_e32 v134, v134
	v_exp_f32_e32 v135, v135
	s_waitcnt lgkmcnt(4)
	v_mfma_f32_32x32x16_bf16 v[144:159], v[244:247], v[176:179], v[144:159]
	ds_read_b64_tr_b16 v[244:245], v234 offset:12800
	ds_read_b64_tr_b16 v[246:247], v234 offset:14848
	v_add_f32_e32 v204, v204, v134
	v_add_f32_e32 v204, v204, v135
	v_cvt_pk_bf16_f32 v187, v134, v135
	v_fmamk_f32 v136, v136, 0x3fb8aa3b, v233
	v_fmamk_f32 v137, v137, 0x3fb8aa3b, v233
	s_waitcnt lgkmcnt(5)
	v_mfma_f32_32x32x16_bf16 v[144:159], v[218:221], v[172:175], v[144:159]
	ds_read_b64_tr_b16 v[218:219], v234 offset:13312
	ds_read_b64_tr_b16 v[220:221], v234 offset:15360
	v_exp_f32_e32 v136, v136
	v_exp_f32_e32 v137, v137
	v_add_f32_e32 v204, v204, v136
	v_add_f32_e32 v204, v204, v137
	v_cvt_pk_bf16_f32 v188, v136, v137
	s_waitcnt lgkmcnt(6)
	v_mfma_f32_32x32x16_bf16 v[144:159], v[210:213], v[168:171], v[144:159]
	ds_read_b64_tr_b16 v[210:211], v234 offset:13824
	ds_read_b64_tr_b16 v[212:213], v234 offset:15872
	v_fmamk_f32 v138, v138, 0x3fb8aa3b, v233
	v_fmamk_f32 v139, v139, 0x3fb8aa3b, v233
	v_exp_f32_e32 v138, v138
	v_exp_f32_e32 v139, v139
	v_add_f32_e32 v204, v204, v138
	s_waitcnt lgkmcnt(6)
	v_mfma_f32_32x32x16_bf16 v[0:15], v[196:199], v[240:243], v[0:15]
	ds_read_b128 v[240:243], v239 offset:40960
	v_add_f32_e32 v204, v204, v139
	v_cvt_pk_bf16_f32 v189, v138, v139
	v_fmamk_f32 v140, v140, 0x3fb8aa3b, v233
	v_fmamk_f32 v141, v141, 0x3fb8aa3b, v233
	s_waitcnt lgkmcnt(5)
	v_mfma_f32_32x32x16_bf16 v[16:31], v[196:199], v[244:247], v[16:31]
	ds_read_b128 v[244:247], v238 offset:40960
	v_exp_f32_e32 v140, v140
	v_exp_f32_e32 v141, v141
	v_add_f32_e32 v204, v204, v140
	v_add_f32_e32 v204, v204, v141
	s_waitcnt lgkmcnt(4)
	v_mfma_f32_32x32x16_bf16 v[32:47], v[196:199], v[218:221], v[32:47]
	ds_read_b128 v[218:221], v237 offset:40960
	v_cvt_pk_bf16_f32 v190, v140, v141
	v_fmamk_f32 v142, v142, 0x3fb8aa3b, v233
	v_fmamk_f32 v143, v143, 0x3fb8aa3b, v233
	v_exp_f32_e32 v142, v142
	s_waitcnt lgkmcnt(3)
	v_mfma_f32_32x32x16_bf16 v[48:63], v[196:199], v[210:213], v[48:63]
	ds_read_b128 v[210:213], v230 offset:0
	v_exp_f32_e32 v143, v143
	v_add_f32_e32 v204, v204, v142
	v_add_f32_e32 v204, v204, v143
	v_cvt_pk_bf16_f32 v191, v142, v143
	s_waitcnt vmcnt(4)
	s_barrier
	s_waitcnt lgkmcnt(3)
	v_mfma_f32_32x32x16_bf16 v[128:143], v[240:243], v[164:167], 0
	ds_read_b128 v[240:243], v235 offset:40960
	v_fmamk_f32 v144, v144, 0x3fb8aa3b, v233
	v_fmamk_f32 v145, v145, 0x3fb8aa3b, v233
	v_exp_f32_e32 v144, v144
	v_exp_f32_e32 v145, v145
	v_add_f32_e32 v204, v204, v144
	s_add_u32 m0, s7, 0x4000
	s_nop 0
	global_load_lds_dwordx4 v249, s[98:99]
	s_waitcnt lgkmcnt(3)
	v_mfma_f32_32x32x16_bf16 v[128:143], v[244:247], v[160:163], v[128:143]
	ds_read_b128 v[244:247], v230 offset:4096
	v_add_f32_e32 v204, v204, v145
	v_cvt_pk_bf16_f32 v192, v144, v145
	v_fmamk_f32 v146, v146, 0x3fb8aa3b, v233
	v_fmamk_f32 v147, v147, 0x3fb8aa3b, v233
	v_exp_f32_e32 v146, v146
	s_add_u32 m0, s7, 0x5000
	s_add_u32 s18, s98, 0x16000
	s_addc_u32 s19, s99, 0
	global_load_lds_dwordx4 v249, s[18:19]
	s_waitcnt lgkmcnt(2)
	v_mfma_f32_32x32x16_bf16 v[128:143], v[218:221], v[210:213], v[128:143]
	ds_read_b64_tr_b16 v[218:219], v234 offset:32768
	ds_read_b64_tr_b16 v[220:221], v234 offset:34816
	ds_read_b64_tr_b16 v[210:211], v234 offset:33280
	ds_read_b64_tr_b16 v[212:213], v234 offset:35328
	v_exp_f32_e32 v147, v147
	v_add_f32_e32 v204, v204, v146
	v_add_f32_e32 v204, v204, v147
	v_cvt_pk_bf16_f32 v193, v146, v147
	v_fmamk_f32 v148, v148, 0x3fb8aa3b, v233
	s_add_u32 m0, s7, 0x6000
	s_add_u32 s18, s98, 0x2c000
	s_addc_u32 s19, s99, 0
	global_load_lds_dwordx4 v249, s[18:19]
	s_waitcnt lgkmcnt(4)
	v_mfma_f32_32x32x16_bf16 v[128:143], v[240:243], v[244:247], v[128:143]
	ds_read_b64_tr_b16 v[240:241], v234 offset:33792
	ds_read_b64_tr_b16 v[242:243], v234 offset:35840
	ds_read_b64_tr_b16 v[244:245], v234 offset:34304
	ds_read_b64_tr_b16 v[246:247], v234 offset:36352
	v_fmamk_f32 v149, v149, 0x3fb8aa3b, v233
	v_exp_f32_e32 v148, v148
	v_exp_f32_e32 v149, v149
	v_add_f32_e32 v204, v204, v148
	v_add_f32_e32 v204, v204, v149
	s_add_u32 m0, s7, 0x7000
	s_add_u32 s18, s98, 0x42000
	s_addc_u32 s19, s99, 0
	global_load_lds_dwordx4 v249, s[18:19]
	s_add_u32 s98, s98, 0x58000
	s_addc_u32 s99, s99, 0
	s_waitcnt lgkmcnt(6)
	v_mfma_f32_32x32x16_bf16 v[64:79], v[184:187], v[218:221], v[64:79]
	ds_read_b64_tr_b16 v[218:219], v234 offset:36864
	ds_read_b64_tr_b16 v[220:221], v234 offset:38912
	v_cvt_pk_bf16_f32 v194, v148, v149
	v_fmamk_f32 v150, v150, 0x3fb8aa3b, v233
	v_fmamk_f32 v151, v151, 0x3fb8aa3b, v233
	v_exp_f32_e32 v150, v150
	v_exp_f32_e32 v151, v151
	s_waitcnt lgkmcnt(6)
	v_mfma_f32_32x32x16_bf16 v[80:95], v[184:187], v[210:213], v[80:95]
	ds_read_b64_tr_b16 v[210:211], v234 offset:37376
	ds_read_b64_tr_b16 v[212:213], v234 offset:39424
	v_add_f32_e32 v204, v204, v150
	v_add_f32_e32 v204, v204, v151
	v_cvt_pk_bf16_f32 v195, v150, v151
	v_fmamk_f32 v152, v152, 0x3fb8aa3b, v233
	v_fmamk_f32 v153, v153, 0x3fb8aa3b, v233
	s_waitcnt lgkmcnt(6)
	v_mfma_f32_32x32x16_bf16 v[96:111], v[184:187], v[240:243], v[96:111]
	ds_read_b64_tr_b16 v[240:241], v234 offset:37888
	ds_read_b64_tr_b16 v[242:243], v234 offset:39936
	v_exp_f32_e32 v152, v152
	v_exp_f32_e32 v153, v153
	v_add_f32_e32 v204, v204, v152
	v_add_f32_e32 v204, v204, v153
	v_cvt_pk_bf16_f32 v196, v152, v153
	s_waitcnt lgkmcnt(6)
; #define SBAR() __builtin_amdgcn_sched_barrier(0)
; template <int D0> __device__ __forceinline__ void pv_two(f32x16& oa, f32x16& ob, int vb, bf16x8 a0, bf16x8 a1, bf16x8 a2, bf16x8 a3,
;                                                          bf16x8 b0, bf16x8 b1, bf16x8 b2, bf16x8 b3) {
;     ...
;   { const s16x4 l0 = tr_read<v_rd_off(D0, 0, 0)>(vb), h0 = tr_read<v_rd_off(D0, 0, 1)>(vb), l1 = tr_read<v_rd_off(D0, 1, 0)>(vb), h1 = tr_read<v_rd_off(D0, 1, 1)>(vb);
;     asm volatile("s_waitcnt lgkmcnt(0)" ::: "memory"); SBAR();
;     const bf16x8 v0 = PKV(l0, h0), v1 = PKV(l1, h1);
;     oa = MFMA(a0, v0, oa); ob = MFMA(b0, v0, ob); oa = MFMA(a1, v1, oa); ob = MFMA(b1, v1, ob); }
;   { const s16x4 l2 = tr_read<v_rd_off(D0, 2, 0)>(vb), h2 = tr_read<v_rd_off(D0, 2, 1)>(vb), l3 = tr_read<v_rd_off(D0, 3, 0)>(vb), h3 = tr_read<v_rd_off(D0, 3, 1)>(vb);
;     asm volatile("s_waitcnt lgkmcnt(0)" ::: "memory"); SBAR();
;     const bf16x8 v2 = PKV(l2, h2), v3 = PKV(l3, h3);
;     oa = MFMA(a2, v2, oa); ob = MFMA(b2, v2, ob); oa = MFMA(a3, v3, oa); ob = MFMA(b3, v3, ob); }
;     ...
; }
; __device__ __forceinline__ void att_qkt(f32x16& p0, f32x16& p1, const char* Kb, const bf16x8 (&qr)[4], int koff, int ksw, int hi) {
;   p0 = f32x16{}; p1 = f32x16{};
; #pragma unroll
;   for (int d0 = 0; d0 < 4; ++d0) {
;     const int co = ((d0 * 2 + hi) ^ ksw) << 4;
;     const bf16x8 b0 = *(const bf16x8*)(Kb + koff + co);
;     const bf16x8 b1 = *(const bf16x8*)(Kb + koff + 4096 + co);
;     p0 = MFMA(b0, qr[d0], p0); p1 = MFMA(b1, qr[d0], p1);
;   }
; }
; __device__ __forceinline__ void sm_fixed(f32x16& p0, f32x16& p1, float mC, float& l_reg, bf16x8& pa0, bf16x8& pa1, bf16x8& pa2, bf16x8& pa3) {
;   constexpr float C = 1.4426950408889634f;
; #pragma unroll
;   for (int r = 0; r < 16; ++r) p0[r] = __builtin_amdgcn_exp2f(fmaf(p0[r], C, -mC));
; #pragma unroll
;   for (int r = 0; r < 16; ++r) p1[r] = __builtin_amdgcn_exp2f(fmaf(p1[r], C, -mC));
;   float ps = 0;
; #pragma unroll
;   for (int r = 0; r < 16; ++r) ps += p0[r];
; #pragma unroll
;   for (int r = 0; r < 16; ++r) ps += p1[r];
;   { auto rr = __builtin_amdgcn_permlane32_swap(__float_as_uint(ps), __float_as_uint(ps), false, false);
;     ps = __uint_as_float(rr[0]) + __uint_as_float(rr[1]); }
;   l_reg += ps;
;     ...
;   PK4N(p0, 0, pa0); PK4N(p0, 8, pa1); PK4N(p1, 0, pa2); PK4N(p1, 8, pa3);
;     ...
; }
; #pragma unroll
	v_mfma_f32_32x32x16_bf16 v[112:127], v[184:187], v[244:247], v[112:127]
	ds_read_b64_tr_b16 v[244:245], v234 offset:38400
	ds_read_b64_tr_b16 v[246:247], v234 offset:40448
	v_fmamk_f32 v154, v154, 0x3fb8aa3b, v233
	v_fmamk_f32 v155, v155, 0x3fb8aa3b, v233
	v_exp_f32_e32 v154, v154
	v_exp_f32_e32 v155, v155
	v_add_f32_e32 v204, v204, v154
	s_waitcnt lgkmcnt(6)
	v_mfma_f32_32x32x16_bf16 v[64:79], v[188:191], v[218:221], v[64:79]
	ds_read_b64_tr_b16 v[218:219], v234 offset:40960
	ds_read_b64_tr_b16 v[220:221], v234 offset:43008
	v_add_f32_e32 v204, v204, v155
	v_cvt_pk_bf16_f32 v197, v154, v155
	v_fmamk_f32 v156, v156, 0x3fb8aa3b, v233
	v_fmamk_f32 v157, v157, 0x3fb8aa3b, v233
	s_waitcnt lgkmcnt(6)
	v_mfma_f32_32x32x16_bf16 v[80:95], v[188:191], v[210:213], v[80:95]
	ds_read_b64_tr_b16 v[210:211], v234 offset:41472
	ds_read_b64_tr_b16 v[212:213], v234 offset:43520
	v_exp_f32_e32 v156, v156
	v_exp_f32_e32 v157, v157
	v_add_f32_e32 v204, v204, v156
	v_add_f32_e32 v204, v204, v157
	s_waitcnt lgkmcnt(6)
	v_mfma_f32_32x32x16_bf16 v[96:111], v[188:191], v[240:243], v[96:111]
	ds_read_b64_tr_b16 v[240:241], v234 offset:41984
	ds_read_b64_tr_b16 v[242:243], v234 offset:44032
	v_cvt_pk_bf16_f32 v198, v156, v157
	v_fmamk_f32 v158, v158, 0x3fb8aa3b, v233
	v_fmamk_f32 v159, v159, 0x3fb8aa3b, v233
	v_exp_f32_e32 v158, v158
	s_waitcnt lgkmcnt(6)
	v_mfma_f32_32x32x16_bf16 v[112:127], v[188:191], v[244:247], v[112:127]
	ds_read_b64_tr_b16 v[244:245], v234 offset:42496
	ds_read_b64_tr_b16 v[246:247], v234 offset:44544
	v_exp_f32_e32 v159, v159
	v_add_f32_e32 v204, v204, v158
	v_add_f32_e32 v204, v204, v159
	v_cvt_pk_bf16_f32 v199, v158, v159
	s_waitcnt lgkmcnt(6)
	v_mfma_f32_32x32x16_bf16 v[64:79], v[192:195], v[218:221], v[64:79]
	ds_read_b128 v[218:221], v239 offset:45056
	v_fmamk_f32 v128, v128, 0x3fb8aa3b, v231
	v_fmamk_f32 v129, v129, 0x3fb8aa3b, v231
	v_exp_f32_e32 v128, v128
	v_exp_f32_e32 v129, v129
	v_add_f32_e32 v205, v205, v128
	s_waitcnt lgkmcnt(5)
	v_mfma_f32_32x32x16_bf16 v[80:95], v[192:195], v[210:213], v[80:95]
	ds_read_b128 v[210:213], v238 offset:45056
	v_add_f32_e32 v205, v205, v129
	v_cvt_pk_bf16_f32 v184, v128, v129
	v_fmamk_f32 v130, v130, 0x3fb8aa3b, v231
	v_fmamk_f32 v131, v131, 0x3fb8aa3b, v231
	v_exp_f32_e32 v130, v130
	s_waitcnt lgkmcnt(4)
	v_mfma_f32_32x32x16_bf16 v[96:111], v[192:195], v[240:243], v[96:111]
	ds_read_b128 v[240:243], v237 offset:45056
	v_exp_f32_e32 v131, v131
	v_add_f32_e32 v205, v205, v130
	v_add_f32_e32 v205, v205, v131
	v_cvt_pk_bf16_f32 v185, v130, v131
	v_fmamk_f32 v132, v132, 0x3fb8aa3b, v231
	s_waitcnt lgkmcnt(3)
	v_mfma_f32_32x32x16_bf16 v[112:127], v[192:195], v[244:247], v[112:127]
	ds_read_b128 v[244:247], v230 offset:0
	v_fmamk_f32 v133, v133, 0x3fb8aa3b, v231
	v_exp_f32_e32 v132, v132
	v_exp_f32_e32 v133, v133
	v_add_f32_e32 v205, v205, v132
	v_add_f32_e32 v205, v205, v133
	s_waitcnt lgkmcnt(3)
	v_mfma_f32_32x32x16_bf16 v[144:159], v[218:221], v[164:167], 0
	ds_read_b128 v[218:221], v235 offset:45056
	v_cvt_pk_bf16_f32 v186, v132, v133
	v_fmamk_f32 v134, v134, 0x3fb8aa3b, v231
	v_fmamk_f32 v135, v135, 0x3fb8aa3b, v231
	v_exp_f32_e32 v134, v134
	v_exp_f32_e32 v135, v135
	s_waitcnt lgkmcnt(3)
	v_mfma_f32_32x32x16_bf16 v[144:159], v[210:213], v[160:163], v[144:159]
	ds_read_b128 v[210:213], v230 offset:4096
	v_add_f32_e32 v205, v205, v134
	v_add_f32_e32 v205, v205, v135
	v_cvt_pk_bf16_f32 v187, v134, v135
	v_fmamk_f32 v136, v136, 0x3fb8aa3b, v231
	v_fmamk_f32 v137, v137, 0x3fb8aa3b, v231
	s_waitcnt lgkmcnt(2)
	v_mfma_f32_32x32x16_bf16 v[144:159], v[240:243], v[244:247], v[144:159]
	ds_read_b64_tr_b16 v[240:241], v234 offset:45056
	ds_read_b64_tr_b16 v[242:243], v234 offset:47104
	ds_read_b64_tr_b16 v[244:245], v234 offset:45568
	ds_read_b64_tr_b16 v[246:247], v234 offset:47616
	v_exp_f32_e32 v136, v136
	v_exp_f32_e32 v137, v137
	v_add_f32_e32 v205, v205, v136
	v_add_f32_e32 v205, v205, v137
	v_cvt_pk_bf16_f32 v188, v136, v137
	s_waitcnt lgkmcnt(4)
	v_mfma_f32_32x32x16_bf16 v[144:159], v[218:221], v[210:213], v[144:159]
	ds_read_b64_tr_b16 v[218:219], v234 offset:46080
	ds_read_b64_tr_b16 v[220:221], v234 offset:48128
	ds_read_b64_tr_b16 v[210:211], v234 offset:46592
	ds_read_b64_tr_b16 v[212:213], v234 offset:48640
	v_fmamk_f32 v138, v138, 0x3fb8aa3b, v231
	v_fmamk_f32 v139, v139, 0x3fb8aa3b, v231
	v_exp_f32_e32 v138, v138
	v_exp_f32_e32 v139, v139
	v_add_f32_e32 v205, v205, v138
	s_waitcnt lgkmcnt(6)
	v_mfma_f32_32x32x16_bf16 v[64:79], v[196:199], v[240:243], v[64:79]
	ds_read_b64_tr_b16 v[240:241], v234 offset:32768
	ds_read_b64_tr_b16 v[242:243], v234 offset:34816
	v_add_f32_e32 v205, v205, v139
	v_cvt_pk_bf16_f32 v189, v138, v139
	v_fmamk_f32 v140, v140, 0x3fb8aa3b, v231
	v_fmamk_f32 v141, v141, 0x3fb8aa3b, v231
	s_waitcnt lgkmcnt(6)
	v_mfma_f32_32x32x16_bf16 v[80:95], v[196:199], v[244:247], v[80:95]
	ds_read_b64_tr_b16 v[244:245], v234 offset:33280
	ds_read_b64_tr_b16 v[246:247], v234 offset:35328
	v_exp_f32_e32 v140, v140
	v_exp_f32_e32 v141, v141
	v_add_f32_e32 v205, v205, v140
	v_add_f32_e32 v205, v205, v141
	s_waitcnt lgkmcnt(6)
	v_mfma_f32_32x32x16_bf16 v[96:111], v[196:199], v[218:221], v[96:111]
	ds_read_b64_tr_b16 v[218:219], v234 offset:33792
	ds_read_b64_tr_b16 v[220:221], v234 offset:35840
	v_cvt_pk_bf16_f32 v190, v140, v141
	v_fmamk_f32 v142, v142, 0x3fb8aa3b, v231
	v_fmamk_f32 v143, v143, 0x3fb8aa3b, v231
	v_exp_f32_e32 v142, v142
	s_waitcnt lgkmcnt(6)
	v_mfma_f32_32x32x16_bf16 v[112:127], v[196:199], v[210:213], v[112:127]
	ds_read_b64_tr_b16 v[210:211], v234 offset:34304
	ds_read_b64_tr_b16 v[212:213], v234 offset:36352
	v_exp_f32_e32 v143, v143
	v_add_f32_e32 v205, v205, v142
	v_add_f32_e32 v205, v205, v143
	v_cvt_pk_bf16_f32 v191, v142, v143
	s_waitcnt vmcnt(4)
	s_barrier
; #define SBAR() __builtin_amdgcn_sched_barrier(0)
; template <int D0> __device__ __forceinline__ void pv_two(f32x16& oa, f32x16& ob, int vb, bf16x8 a0, bf16x8 a1, bf16x8 a2, bf16x8 a3,
;                                                          bf16x8 b0, bf16x8 b1, bf16x8 b2, bf16x8 b3) {
;     ...
;   { const s16x4 l0 = tr_read<v_rd_off(D0, 0, 0)>(vb), h0 = tr_read<v_rd_off(D0, 0, 1)>(vb), l1 = tr_read<v_rd_off(D0, 1, 0)>(vb), h1 = tr_read<v_rd_off(D0, 1, 1)>(vb);
;     asm volatile("s_waitcnt lgkmcnt(0)" ::: "memory"); SBAR();
;     const bf16x8 v0 = PKV(l0, h0), v1 = PKV(l1, h1);
;     oa = MFMA(a0, v0, oa); ob = MFMA(b0, v0, ob); oa = MFMA(a1, v1, oa); ob = MFMA(b1, v1, ob); }
;   { const s16x4 l2 = tr_read<v_rd_off(D0, 2, 0)>(vb), h2 = tr_read<v_rd_off(D0, 2, 1)>(vb), l3 = tr_read<v_rd_off(D0, 3, 0)>(vb), h3 = tr_read<v_rd_off(D0, 3, 1)>(vb);
;     asm volatile("s_waitcnt lgkmcnt(0)" ::: "memory"); SBAR();
;     const bf16x8 v2 = PKV(l2, h2), v3 = PKV(l3, h3);
;     oa = MFMA(a2, v2, oa); ob = MFMA(b2, v2, ob); oa = MFMA(a3, v3, oa); ob = MFMA(b3, v3, ob); }
;     ...
; }
; __device__ __forceinline__ void att_qkt(f32x16& p0, f32x16& p1, const char* Kb, const bf16x8 (&qr)[4], int koff, int ksw, int hi) {
;   p0 = f32x16{}; p1 = f32x16{};
; #pragma unroll
;   for (int d0 = 0; d0 < 4; ++d0) {
;     const int co = ((d0 * 2 + hi) ^ ksw) << 4;
;     const bf16x8 b0 = *(const bf16x8*)(Kb + koff + co);
;     const bf16x8 b1 = *(const bf16x8*)(Kb + koff + 4096 + co);
;     p0 = MFMA(b0, qr[d0], p0); p1 = MFMA(b1, qr[d0], p1);
;   }
; }
; __device__ __forceinline__ void sm_fixed(f32x16& p0, f32x16& p1, float mC, float& l_reg, bf16x8& pa0, bf16x8& pa1, bf16x8& pa2, bf16x8& pa3) {
;   constexpr float C = 1.4426950408889634f;
; #pragma unroll
;   for (int r = 0; r < 16; ++r) p0[r] = __builtin_amdgcn_exp2f(fmaf(p0[r], C, -mC));
; #pragma unroll
;   for (int r = 0; r < 16; ++r) p1[r] = __builtin_amdgcn_exp2f(fmaf(p1[r], C, -mC));
;   float ps = 0;
; #pragma unroll
;   for (int r = 0; r < 16; ++r) ps += p0[r];
; #pragma unroll
;   for (int r = 0; r < 16; ++r) ps += p1[r];
;   { auto rr = __builtin_amdgcn_permlane32_swap(__float_as_uint(ps), __float_as_uint(ps), false, false);
;     ps = __uint_as_float(rr[0]) + __uint_as_float(rr[1]); }
;   l_reg += ps;
;     ...
;   PK4N(p0, 0, pa0); PK4N(p0, 8, pa1); PK4N(p1, 0, pa2); PK4N(p1, 8, pa3);
;     ...
; }
	s_waitcnt lgkmcnt(6)
	v_mfma_f32_32x32x16_bf16 v[0:15], v[184:187], v[240:243], v[0:15]
	ds_read_b128 v[240:243], v239 offset:0
	v_fmamk_f32 v144, v144, 0x3fb8aa3b, v231
	v_fmamk_f32 v145, v145, 0x3fb8aa3b, v231
	v_exp_f32_e32 v144, v144
	v_exp_f32_e32 v145, v145
	v_add_f32_e32 v205, v205, v144
	s_add_u32 m0, s7, 0x8000
	s_nop 0
	global_load_lds_dwordx4 v248, s[40:41]
	s_waitcnt lgkmcnt(5)
	v_mfma_f32_32x32x16_bf16 v[16:31], v[184:187], v[244:247], v[16:31]
	ds_read_b128 v[244:247], v238 offset:0
	v_add_f32_e32 v205, v205, v145
	v_cvt_pk_bf16_f32 v192, v144, v145
	v_fmamk_f32 v146, v146, 0x3fb8aa3b, v231
	v_fmamk_f32 v147, v147, 0x3fb8aa3b, v231
	v_exp_f32_e32 v146, v146
	s_add_u32 m0, s7, 0xa000
	s_add_u32 s18, s40, 0x80
	s_addc_u32 s19, s41, 0
	global_load_lds_dwordx4 v248, s[18:19]
	s_waitcnt lgkmcnt(4)
	v_mfma_f32_32x32x16_bf16 v[32:47], v[184:187], v[218:221], v[32:47]
	ds_read_b128 v[218:221], v237 offset:0
	v_exp_f32_e32 v147, v147
	v_add_f32_e32 v205, v205, v146
	v_add_f32_e32 v205, v205, v147
	v_cvt_pk_bf16_f32 v193, v146, v147
	v_fmamk_f32 v148, v148, 0x3fb8aa3b, v231
	s_add_u32 m0, s7, 0x9000
	s_add_u32 s18, s40, 0x2c000
	s_addc_u32 s19, s41, 0
	global_load_lds_dwordx4 v248, s[18:19]
	s_waitcnt lgkmcnt(3)
	v_mfma_f32_32x32x16_bf16 v[48:63], v[184:187], v[210:213], v[48:63]
	ds_read_b128 v[210:213], v235 offset:0
	v_fmamk_f32 v149, v149, 0x3fb8aa3b, v231
	v_exp_f32_e32 v148, v148
	v_exp_f32_e32 v149, v149
	v_add_f32_e32 v205, v205, v148
	v_add_f32_e32 v205, v205, v149
	s_add_u32 m0, s7, 0xb000
	s_add_u32 s18, s40, 0x2c080
	s_addc_u32 s19, s41, 0
	global_load_lds_dwordx4 v248, s[18:19]
	s_add_u32 s40, s40, 0x58000
	s_addc_u32 s41, s41, 0
	s_waitcnt lgkmcnt(3)
	v_mfma_f32_32x32x16_bf16 v[128:143], v[240:243], v[180:183], 0
	ds_read_b64_tr_b16 v[240:241], v234 offset:36864
	ds_read_b64_tr_b16 v[242:243], v234 offset:38912
	v_cvt_pk_bf16_f32 v194, v148, v149
	v_fmamk_f32 v150, v150, 0x3fb8aa3b, v231
	v_fmamk_f32 v151, v151, 0x3fb8aa3b, v231
	v_exp_f32_e32 v150, v150
	v_exp_f32_e32 v151, v151
	s_waitcnt lgkmcnt(4)
	v_mfma_f32_32x32x16_bf16 v[128:143], v[244:247], v[176:179], v[128:143]
	ds_read_b64_tr_b16 v[244:245], v234 offset:37376
	ds_read_b64_tr_b16 v[246:247], v234 offset:39424
	v_add_f32_e32 v205, v205, v150
	v_add_f32_e32 v205, v205, v151
	v_cvt_pk_bf16_f32 v195, v150, v151
	v_fmamk_f32 v152, v152, 0x3fb8aa3b, v231
	v_fmamk_f32 v153, v153, 0x3fb8aa3b, v231
	s_waitcnt lgkmcnt(5)
	v_mfma_f32_32x32x16_bf16 v[128:143], v[218:221], v[172:175], v[128:143]
	ds_read_b64_tr_b16 v[218:219], v234 offset:37888
	ds_read_b64_tr_b16 v[220:221], v234 offset:39936
	v_exp_f32_e32 v152, v152
	v_exp_f32_e32 v153, v153
	v_add_f32_e32 v205, v205, v152
	v_add_f32_e32 v205, v205, v153
	v_cvt_pk_bf16_f32 v196, v152, v153
	s_waitcnt lgkmcnt(6)
	v_mfma_f32_32x32x16_bf16 v[128:143], v[210:213], v[168:171], v[128:143]
	ds_read_b64_tr_b16 v[210:211], v234 offset:38400
	ds_read_b64_tr_b16 v[212:213], v234 offset:40448
	v_fmamk_f32 v154, v154, 0x3fb8aa3b, v231
	v_fmamk_f32 v155, v155, 0x3fb8aa3b, v231
	v_exp_f32_e32 v154, v154
	v_exp_f32_e32 v155, v155
	v_add_f32_e32 v205, v205, v154
	s_waitcnt lgkmcnt(6)
	v_mfma_f32_32x32x16_bf16 v[0:15], v[188:191], v[240:243], v[0:15]
	ds_read_b64_tr_b16 v[240:241], v234 offset:40960
	ds_read_b64_tr_b16 v[242:243], v234 offset:43008
	v_add_f32_e32 v205, v205, v155
	v_cvt_pk_bf16_f32 v197, v154, v155
	v_fmamk_f32 v156, v156, 0x3fb8aa3b, v231
	v_fmamk_f32 v157, v157, 0x3fb8aa3b, v231
	s_waitcnt lgkmcnt(6)
	v_mfma_f32_32x32x16_bf16 v[16:31], v[188:191], v[244:247], v[16:31]
	ds_read_b64_tr_b16 v[244:245], v234 offset:41472
	ds_read_b64_tr_b16 v[246:247], v234 offset:43520
	v_exp_f32_e32 v156, v156
	v_exp_f32_e32 v157, v157
	v_add_f32_e32 v205, v205, v156
	v_add_f32_e32 v205, v205, v157
	s_waitcnt lgkmcnt(6)
	v_mfma_f32_32x32x16_bf16 v[32:47], v[188:191], v[218:221], v[32:47]
	ds_read_b64_tr_b16 v[218:219], v234 offset:41984
	ds_read_b64_tr_b16 v[220:221], v234 offset:44032
	v_cvt_pk_bf16_f32 v198, v156, v157
	v_fmamk_f32 v158, v158, 0x3fb8aa3b, v231
	v_fmamk_f32 v159, v159, 0x3fb8aa3b, v231
	v_exp_f32_e32 v158, v158
	s_waitcnt lgkmcnt(6)
	v_mfma_f32_32x32x16_bf16 v[48:63], v[188:191], v[210:213], v[48:63]
	ds_read_b64_tr_b16 v[210:211], v234 offset:42496
	ds_read_b64_tr_b16 v[212:213], v234 offset:44544
	v_exp_f32_e32 v159, v159
	v_add_f32_e32 v205, v205, v158
	v_add_f32_e32 v205, v205, v159
	v_cvt_pk_bf16_f32 v199, v158, v159
	s_waitcnt lgkmcnt(6)
	v_mfma_f32_32x32x16_bf16 v[0:15], v[192:195], v[240:243], v[0:15]
	ds_read_b128 v[240:243], v239 offset:4096
	v_fmamk_f32 v128, v128, 0x3fb8aa3b, v233
	v_fmamk_f32 v129, v129, 0x3fb8aa3b, v233
	v_exp_f32_e32 v128, v128
	v_exp_f32_e32 v129, v129
	v_add_f32_e32 v204, v204, v128
	s_waitcnt lgkmcnt(5)
	v_mfma_f32_32x32x16_bf16 v[16:31], v[192:195], v[244:247], v[16:31]
	ds_read_b128 v[244:247], v238 offset:4096
	v_add_f32_e32 v204, v204, v129
	v_cvt_pk_bf16_f32 v184, v128, v129
	v_fmamk_f32 v130, v130, 0x3fb8aa3b, v233
	v_fmamk_f32 v131, v131, 0x3fb8aa3b, v233
	v_exp_f32_e32 v130, v130
	s_waitcnt lgkmcnt(4)
	v_mfma_f32_32x32x16_bf16 v[32:47], v[192:195], v[218:221], v[32:47]
	ds_read_b128 v[218:221], v237 offset:4096
	v_exp_f32_e32 v131, v131
	v_add_f32_e32 v204, v204, v130
	v_add_f32_e32 v204, v204, v131
	v_cvt_pk_bf16_f32 v185, v130, v131
	v_fmamk_f32 v132, v132, 0x3fb8aa3b, v233
	s_waitcnt lgkmcnt(3)
	v_mfma_f32_32x32x16_bf16 v[48:63], v[192:195], v[210:213], v[48:63]
	ds_read_b128 v[210:213], v235 offset:4096
	v_fmamk_f32 v133, v133, 0x3fb8aa3b, v233
	v_exp_f32_e32 v132, v132
	v_exp_f32_e32 v133, v133
	v_add_f32_e32 v204, v204, v132
	v_add_f32_e32 v204, v204, v133
	s_waitcnt lgkmcnt(3)
; #define SBAR() __builtin_amdgcn_sched_barrier(0)
; template <int D0> __device__ __forceinline__ void pv_two(f32x16& oa, f32x16& ob, int vb, bf16x8 a0, bf16x8 a1, bf16x8 a2, bf16x8 a3,
;                                                          bf16x8 b0, bf16x8 b1, bf16x8 b2, bf16x8 b3) {
;     ...
;   { const s16x4 l0 = tr_read<v_rd_off(D0, 0, 0)>(vb), h0 = tr_read<v_rd_off(D0, 0, 1)>(vb), l1 = tr_read<v_rd_off(D0, 1, 0)>(vb), h1 = tr_read<v_rd_off(D0, 1, 1)>(vb);
;     asm volatile("s_waitcnt lgkmcnt(0)" ::: "memory"); SBAR();
;     const bf16x8 v0 = PKV(l0, h0), v1 = PKV(l1, h1);
;     oa = MFMA(a0, v0, oa); ob = MFMA(b0, v0, ob); oa = MFMA(a1, v1, oa); ob = MFMA(b1, v1, ob); }
;   { const s16x4 l2 = tr_read<v_rd_off(D0, 2, 0)>(vb), h2 = tr_read<v_rd_off(D0, 2, 1)>(vb), l3 = tr_read<v_rd_off(D0, 3, 0)>(vb), h3 = tr_read<v_rd_off(D0, 3, 1)>(vb);
;     asm volatile("s_waitcnt lgkmcnt(0)" ::: "memory"); SBAR();
;     const bf16x8 v2 = PKV(l2, h2), v3 = PKV(l3, h3);
;     oa = MFMA(a2, v2, oa); ob = MFMA(b2, v2, ob); oa = MFMA(a3, v3, oa); ob = MFMA(b3, v3, ob); }
;     ...
; }
; __device__ __forceinline__ void att_qkt(f32x16& p0, f32x16& p1, const char* Kb, const bf16x8 (&qr)[4], int koff, int ksw, int hi) {
;   p0 = f32x16{}; p1 = f32x16{};
; #pragma unroll
;   for (int d0 = 0; d0 < 4; ++d0) {
;     const int co = ((d0 * 2 + hi) ^ ksw) << 4;
;     const bf16x8 b0 = *(const bf16x8*)(Kb + koff + co);
;     const bf16x8 b1 = *(const bf16x8*)(Kb + koff + 4096 + co);
;     p0 = MFMA(b0, qr[d0], p0); p1 = MFMA(b1, qr[d0], p1);
;   }
; }
; __device__ __forceinline__ void sm_fixed(f32x16& p0, f32x16& p1, float mC, float& l_reg, bf16x8& pa0, bf16x8& pa1, bf16x8& pa2, bf16x8& pa3) {
;   constexpr float C = 1.4426950408889634f;
; #pragma unroll
;   for (int r = 0; r < 16; ++r) p0[r] = __builtin_amdgcn_exp2f(fmaf(p0[r], C, -mC));
; #pragma unroll
;   for (int r = 0; r < 16; ++r) p1[r] = __builtin_amdgcn_exp2f(fmaf(p1[r], C, -mC));
;   float ps = 0;
; #pragma unroll
;   for (int r = 0; r < 16; ++r) ps += p0[r];
; #pragma unroll
;   for (int r = 0; r < 16; ++r) ps += p1[r];
;   { auto rr = __builtin_amdgcn_permlane32_swap(__float_as_uint(ps), __float_as_uint(ps), false, false);
;     ps = __uint_as_float(rr[0]) + __uint_as_float(rr[1]); }
;   l_reg += ps;
;     ...
;   PK4N(p0, 0, pa0); PK4N(p0, 8, pa1); PK4N(p1, 0, pa2); PK4N(p1, 8, pa3);
;     ...
; }
; #pragma unroll
	v_mfma_f32_32x32x16_bf16 v[144:159], v[240:243], v[180:183], 0
	ds_read_b64_tr_b16 v[240:241], v234 offset:45056
	ds_read_b64_tr_b16 v[242:243], v234 offset:47104
	v_cvt_pk_bf16_f32 v186, v132, v133
	v_fmamk_f32 v134, v134, 0x3fb8aa3b, v233
	v_fmamk_f32 v135, v135, 0x3fb8aa3b, v233
	v_exp_f32_e32 v134, v134
	v_exp_f32_e32 v135, v135
	s_waitcnt lgkmcnt(4)
	v_mfma_f32_32x32x16_bf16 v[144:159], v[244:247], v[176:179], v[144:159]
	ds_read_b64_tr_b16 v[244:245], v234 offset:45568
	ds_read_b64_tr_b16 v[246:247], v234 offset:47616
	v_add_f32_e32 v204, v204, v134
	v_add_f32_e32 v204, v204, v135
	v_cvt_pk_bf16_f32 v187, v134, v135
	v_fmamk_f32 v136, v136, 0x3fb8aa3b, v233
	v_fmamk_f32 v137, v137, 0x3fb8aa3b, v233
	s_waitcnt lgkmcnt(5)
	v_mfma_f32_32x32x16_bf16 v[144:159], v[218:221], v[172:175], v[144:159]
	ds_read_b64_tr_b16 v[218:219], v234 offset:46080
	ds_read_b64_tr_b16 v[220:221], v234 offset:48128
	v_exp_f32_e32 v136, v136
	v_exp_f32_e32 v137, v137
	v_add_f32_e32 v204, v204, v136
	v_add_f32_e32 v204, v204, v137
	v_cvt_pk_bf16_f32 v188, v136, v137
	s_waitcnt lgkmcnt(6)
	v_mfma_f32_32x32x16_bf16 v[144:159], v[210:213], v[168:171], v[144:159]
	ds_read_b64_tr_b16 v[210:211], v234 offset:46592
	ds_read_b64_tr_b16 v[212:213], v234 offset:48640
	v_fmamk_f32 v138, v138, 0x3fb8aa3b, v233
	v_fmamk_f32 v139, v139, 0x3fb8aa3b, v233
	v_exp_f32_e32 v138, v138
	v_exp_f32_e32 v139, v139
	v_add_f32_e32 v204, v204, v138
	s_waitcnt lgkmcnt(6)
	v_mfma_f32_32x32x16_bf16 v[0:15], v[196:199], v[240:243], v[0:15]
	ds_read_b128 v[240:243], v239 offset:8192
	v_add_f32_e32 v204, v204, v139
	v_cvt_pk_bf16_f32 v189, v138, v139
	v_fmamk_f32 v140, v140, 0x3fb8aa3b, v233
	v_fmamk_f32 v141, v141, 0x3fb8aa3b, v233
	s_waitcnt lgkmcnt(5)
	v_mfma_f32_32x32x16_bf16 v[16:31], v[196:199], v[244:247], v[16:31]
	ds_read_b128 v[244:247], v238 offset:8192
	v_exp_f32_e32 v140, v140
	v_exp_f32_e32 v141, v141
	v_add_f32_e32 v204, v204, v140
	v_add_f32_e32 v204, v204, v141
	s_waitcnt lgkmcnt(4)
	v_mfma_f32_32x32x16_bf16 v[32:47], v[196:199], v[218:221], v[32:47]
	ds_read_b128 v[218:221], v237 offset:8192
	v_cvt_pk_bf16_f32 v190, v140, v141
	v_fmamk_f32 v142, v142, 0x3fb8aa3b, v233
	v_fmamk_f32 v143, v143, 0x3fb8aa3b, v233
	v_exp_f32_e32 v142, v142
	s_waitcnt lgkmcnt(3)
	v_mfma_f32_32x32x16_bf16 v[48:63], v[196:199], v[210:213], v[48:63]
	ds_read_b128 v[210:213], v230 offset:0
	v_exp_f32_e32 v143, v143
	v_add_f32_e32 v204, v204, v142
	v_add_f32_e32 v204, v204, v143
	v_cvt_pk_bf16_f32 v191, v142, v143
	s_branch .Lattn_loop
.Lattn_exit:
	s_waitcnt lgkmcnt(6)
	v_mfma_f32_32x32x16_bf16 v[0:15], v[184:187], v[240:243], v[0:15]
	ds_read_b64_tr_b16 v[240:241], v234 offset:4096
	ds_read_b64_tr_b16 v[242:243], v234 offset:6144
	v_fmamk_f32 v144, v144, 0x3fb8aa3b, v231
	v_fmamk_f32 v145, v145, 0x3fb8aa3b, v231
	v_exp_f32_e32 v144, v144
	v_exp_f32_e32 v145, v145
	v_add_f32_e32 v205, v205, v144
	v_add_f32_e32 v205, v205, v145
	v_cvt_pk_bf16_f32 v192, v144, v145
	s_waitcnt lgkmcnt(6)
	v_mfma_f32_32x32x16_bf16 v[16:31], v[184:187], v[244:247], v[16:31]
	ds_read_b64_tr_b16 v[244:245], v234 offset:4608
	ds_read_b64_tr_b16 v[246:247], v234 offset:6656
	v_fmamk_f32 v146, v146, 0x3fb8aa3b, v231
	v_fmamk_f32 v147, v147, 0x3fb8aa3b, v231
	v_exp_f32_e32 v146, v146
	v_exp_f32_e32 v147, v147
	v_add_f32_e32 v205, v205, v146
	v_add_f32_e32 v205, v205, v147
	v_cvt_pk_bf16_f32 v193, v146, v147
	s_waitcnt lgkmcnt(6)
	v_mfma_f32_32x32x16_bf16 v[32:47], v[184:187], v[218:221], v[32:47]
	ds_read_b64_tr_b16 v[218:219], v234 offset:5120
	ds_read_b64_tr_b16 v[220:221], v234 offset:7168
	v_fmamk_f32 v148, v148, 0x3fb8aa3b, v231
	v_fmamk_f32 v149, v149, 0x3fb8aa3b, v231
	v_exp_f32_e32 v148, v148
	v_exp_f32_e32 v149, v149
	v_add_f32_e32 v205, v205, v148
	v_add_f32_e32 v205, v205, v149
	v_cvt_pk_bf16_f32 v194, v148, v149
	s_waitcnt lgkmcnt(6)
	v_mfma_f32_32x32x16_bf16 v[48:63], v[184:187], v[210:213], v[48:63]
	ds_read_b64_tr_b16 v[210:211], v234 offset:5632
	ds_read_b64_tr_b16 v[212:213], v234 offset:7680
	v_fmamk_f32 v150, v150, 0x3fb8aa3b, v231
	v_fmamk_f32 v151, v151, 0x3fb8aa3b, v231
	v_exp_f32_e32 v150, v150
	v_exp_f32_e32 v151, v151
	v_add_f32_e32 v205, v205, v150
	v_add_f32_e32 v205, v205, v151
	v_cvt_pk_bf16_f32 v195, v150, v151
	s_waitcnt lgkmcnt(6)
	v_mfma_f32_32x32x16_bf16 v[0:15], v[188:191], v[240:243], v[0:15]
	ds_read_b64_tr_b16 v[240:241], v234 offset:8192
	ds_read_b64_tr_b16 v[242:243], v234 offset:10240
	v_fmamk_f32 v152, v152, 0x3fb8aa3b, v231
	v_fmamk_f32 v153, v153, 0x3fb8aa3b, v231
	v_exp_f32_e32 v152, v152
	v_exp_f32_e32 v153, v153
	v_add_f32_e32 v205, v205, v152
	v_add_f32_e32 v205, v205, v153
	v_cvt_pk_bf16_f32 v196, v152, v153
	s_waitcnt lgkmcnt(6)
	v_mfma_f32_32x32x16_bf16 v[16:31], v[188:191], v[244:247], v[16:31]
	ds_read_b64_tr_b16 v[244:245], v234 offset:8704
	ds_read_b64_tr_b16 v[246:247], v234 offset:10752
	v_fmamk_f32 v154, v154, 0x3fb8aa3b, v231
	v_fmamk_f32 v155, v155, 0x3fb8aa3b, v231
	v_exp_f32_e32 v154, v154
	v_exp_f32_e32 v155, v155
	v_add_f32_e32 v205, v205, v154
	v_add_f32_e32 v205, v205, v155
	v_cvt_pk_bf16_f32 v197, v154, v155
	s_waitcnt lgkmcnt(6)
	v_mfma_f32_32x32x16_bf16 v[32:47], v[188:191], v[218:221], v[32:47]
	ds_read_b64_tr_b16 v[218:219], v234 offset:9216
	ds_read_b64_tr_b16 v[220:221], v234 offset:11264
	v_fmamk_f32 v156, v156, 0x3fb8aa3b, v231
	v_fmamk_f32 v157, v157, 0x3fb8aa3b, v231
	v_exp_f32_e32 v156, v156
	v_exp_f32_e32 v157, v157
	v_add_f32_e32 v205, v205, v156
	v_add_f32_e32 v205, v205, v157
	v_cvt_pk_bf16_f32 v198, v156, v157
	s_waitcnt lgkmcnt(6)
; #define SBAR() __builtin_amdgcn_sched_barrier(0)
; template <int D0> __device__ __forceinline__ void pv_two(f32x16& oa, f32x16& ob, int vb, bf16x8 a0, bf16x8 a1, bf16x8 a2, bf16x8 a3,
;                                                          bf16x8 b0, bf16x8 b1, bf16x8 b2, bf16x8 b3) {
;     ...
;   { const s16x4 l0 = tr_read<v_rd_off(D0, 0, 0)>(vb), h0 = tr_read<v_rd_off(D0, 0, 1)>(vb), l1 = tr_read<v_rd_off(D0, 1, 0)>(vb), h1 = tr_read<v_rd_off(D0, 1, 1)>(vb);
;     asm volatile("s_waitcnt lgkmcnt(0)" ::: "memory"); SBAR();
;     const bf16x8 v0 = PKV(l0, h0), v1 = PKV(l1, h1);
;     oa = MFMA(a0, v0, oa); ob = MFMA(b0, v0, ob); oa = MFMA(a1, v1, oa); ob = MFMA(b1, v1, ob); }
;   { const s16x4 l2 = tr_read<v_rd_off(D0, 2, 0)>(vb), h2 = tr_read<v_rd_off(D0, 2, 1)>(vb), l3 = tr_read<v_rd_off(D0, 3, 0)>(vb), h3 = tr_read<v_rd_off(D0, 3, 1)>(vb);
;     asm volatile("s_waitcnt lgkmcnt(0)" ::: "memory"); SBAR();
;     const bf16x8 v2 = PKV(l2, h2), v3 = PKV(l3, h3);
;     oa = MFMA(a2, v2, oa); ob = MFMA(b2, v2, ob); oa = MFMA(a3, v3, oa); ob = MFMA(b3, v3, ob); }
;     ...
; }
; __device__ __forceinline__ void att_qkt(f32x16& p0, f32x16& p1, const char* Kb, const bf16x8 (&qr)[4], int koff, int ksw, int hi) {
;   p0 = f32x16{}; p1 = f32x16{};
; #pragma unroll
;   for (int d0 = 0; d0 < 4; ++d0) {
;     const int co = ((d0 * 2 + hi) ^ ksw) << 4;
;     const bf16x8 b0 = *(const bf16x8*)(Kb + koff + co);
;     const bf16x8 b1 = *(const bf16x8*)(Kb + koff + 4096 + co);
;     p0 = MFMA(b0, qr[d0], p0); p1 = MFMA(b1, qr[d0], p1);
;   }
; }
; __device__ __forceinline__ void sm_fixed(f32x16& p0, f32x16& p1, float mC, float& l_reg, bf16x8& pa0, bf16x8& pa1, bf16x8& pa2, bf16x8& pa3) {
;   constexpr float C = 1.4426950408889634f;
; #pragma unroll
;   for (int r = 0; r < 16; ++r) p0[r] = __builtin_amdgcn_exp2f(fmaf(p0[r], C, -mC));
; #pragma unroll
;   for (int r = 0; r < 16; ++r) p1[r] = __builtin_amdgcn_exp2f(fmaf(p1[r], C, -mC));
;   float ps = 0;
; #pragma unroll
;   for (int r = 0; r < 16; ++r) ps += p0[r];
; #pragma unroll
;   for (int r = 0; r < 16; ++r) ps += p1[r];
;   { auto rr = __builtin_amdgcn_permlane32_swap(__float_as_uint(ps), __float_as_uint(ps), false, false);
;     ps = __uint_as_float(rr[0]) + __uint_as_float(rr[1]); }
;   l_reg += ps;
;     ...
;   PK4N(p0, 0, pa0); PK4N(p0, 8, pa1); PK4N(p1, 0, pa2); PK4N(p1, 8, pa3);
;     ...
; }
	v_mfma_f32_32x32x16_bf16 v[48:63], v[188:191], v[210:213], v[48:63]
	ds_read_b64_tr_b16 v[210:211], v234 offset:9728
	ds_read_b64_tr_b16 v[212:213], v234 offset:11776
	v_fmamk_f32 v158, v158, 0x3fb8aa3b, v231
	v_fmamk_f32 v159, v159, 0x3fb8aa3b, v231
	v_exp_f32_e32 v158, v158
	v_exp_f32_e32 v159, v159
	v_add_f32_e32 v205, v205, v158
	v_add_f32_e32 v205, v205, v159
	v_cvt_pk_bf16_f32 v199, v158, v159
	s_waitcnt lgkmcnt(6)
	v_mfma_f32_32x32x16_bf16 v[0:15], v[192:195], v[240:243], v[0:15]
	ds_read_b64_tr_b16 v[240:241], v234 offset:12288
	ds_read_b64_tr_b16 v[242:243], v234 offset:14336
	s_waitcnt lgkmcnt(6)
	v_mfma_f32_32x32x16_bf16 v[16:31], v[192:195], v[244:247], v[16:31]
	ds_read_b64_tr_b16 v[244:245], v234 offset:12800
	ds_read_b64_tr_b16 v[246:247], v234 offset:14848
	s_waitcnt lgkmcnt(6)
	v_mfma_f32_32x32x16_bf16 v[32:47], v[192:195], v[218:221], v[32:47]
	ds_read_b64_tr_b16 v[218:219], v234 offset:13312
	ds_read_b64_tr_b16 v[220:221], v234 offset:15360
	s_waitcnt lgkmcnt(6)
	v_mfma_f32_32x32x16_bf16 v[48:63], v[192:195], v[210:213], v[48:63]
	ds_read_b64_tr_b16 v[210:211], v234 offset:13824
	ds_read_b64_tr_b16 v[212:213], v234 offset:15872
	s_waitcnt lgkmcnt(6)
	v_mfma_f32_32x32x16_bf16 v[0:15], v[196:199], v[240:243], v[0:15]
	s_waitcnt lgkmcnt(4)
	v_mfma_f32_32x32x16_bf16 v[16:31], v[196:199], v[244:247], v[16:31]
	s_waitcnt lgkmcnt(2)
	v_mfma_f32_32x32x16_bf16 v[32:47], v[196:199], v[218:221], v[32:47]
	s_waitcnt lgkmcnt(0)
	v_mfma_f32_32x32x16_bf16 v[48:63], v[196:199], v[210:213], v[48:63]
	v_sub_u32_e32 v239, v239, v236
	v_sub_u32_e32 v238, v238, v236
	v_sub_u32_e32 v237, v237, v236
	v_sub_u32_e32 v235, v235, v236
	v_mov_b32_e32 v210, v204
	v_mov_b32_e32 v212, v204
	v_mov_b32_e32 v211, v205
	v_mov_b32_e32 v213, v205
	s_nop 1
	v_permlane32_swap_b32_e32 v210, v212
	v_permlane32_swap_b32_e32 v211, v213
	s_nop 1
	v_add_f32_e32 v204, v210, v212
	v_add_f32_e32 v205, v211, v213
	v_add_u32_e32 v198, v236, v239
	s_waitcnt vmcnt(0)
	s_waitcnt vmcnt(0)
	s_barrier
	ds_read_b128 v[128:131], v198 offset:32768
	ds_read_b128 v[132:135], v198 offset:36864
	v_add_u32_e32 v199, v236, v238
	s_waitcnt lgkmcnt(1)
	v_mfma_f32_32x32x16_bf16 v[144:159], v[128:131], v[180:183], 0
	v_add_u32_e32 v206, v236, v237
	ds_read_b128 v[186:189], v199 offset:36864
	v_add_u32_e32 v207, v236, v235
	v_and_b32_e32 v184, 0x3fffffc0, v214
	s_add_i32 s3, 0, 0x10000
	ds_read_b128 v[190:193], v206 offset:36864
	v_lshl_add_u32 v184, v184, 2, s3
	s_waitcnt lgkmcnt(2)
	v_mfma_f32_32x32x16_bf16 v[128:143], v[132:135], v[180:183], 0
	ds_read_b128 v[180:183], v199 offset:32768
	v_add_u32_e32 v185, 0x8000, v234
	ds_read_b128 v[194:197], v207 offset:36864
	s_waitcnt lgkmcnt(1)
	v_mfma_f32_32x32x16_bf16 v[144:159], v[180:183], v[176:179], v[144:159]
	ds_read_b128 v[180:183], v206 offset:32768
	s_waitcnt lgkmcnt(0)
	v_mfma_f32_32x32x16_bf16 v[144:159], v[180:183], v[172:175], v[144:159]
	ds_read_b128 v[180:183], v207 offset:32768
	v_mfma_f32_32x32x16_bf16 v[128:143], v[186:189], v[176:179], v[128:143]
	s_waitcnt lgkmcnt(0)
	v_mfma_f32_32x32x16_bf16 v[144:159], v[180:183], v[168:171], v[144:159]
	v_mfma_f32_32x32x16_bf16 v[128:143], v[190:193], v[172:175], v[128:143]
	s_nop 10
	v_fmamk_f32 v144, v144, 0x3fb8aa3b, v233
	v_fmamk_f32 v145, v145, 0x3fb8aa3b, v233
	v_exp_f32_e32 v144, v144
	v_fmamk_f32 v146, v146, 0x3fb8aa3b, v233
	v_exp_f32_e32 v145, v145
	v_fmamk_f32 v147, v147, 0x3fb8aa3b, v233
	v_exp_f32_e32 v146, v146
	v_fmamk_f32 v148, v148, 0x3fb8aa3b, v233
	v_exp_f32_e32 v147, v147
	v_fmamk_f32 v149, v149, 0x3fb8aa3b, v233
	v_exp_f32_e32 v148, v148
	v_mfma_f32_32x32x16_bf16 v[128:143], v[194:197], v[168:171], v[128:143]
	v_add_f32_e32 v168, 0, v144
	v_fmamk_f32 v150, v150, 0x3fb8aa3b, v233
	v_exp_f32_e32 v149, v149
	v_add_f32_e32 v168, v145, v168
	v_fmamk_f32 v151, v151, 0x3fb8aa3b, v233
	v_exp_f32_e32 v150, v150
	v_add_f32_e32 v168, v146, v168
	v_fmamk_f32 v152, v152, 0x3fb8aa3b, v233
	v_exp_f32_e32 v151, v151
	v_add_f32_e32 v168, v147, v168
	v_exp_f32_e32 v152, v152
	v_fmamk_f32 v153, v153, 0x3fb8aa3b, v233
	v_add_f32_e32 v168, v148, v168
	v_exp_f32_e32 v153, v153
	v_fmamk_f32 v154, v154, 0x3fb8aa3b, v233
	v_add_f32_e32 v168, v149, v168
	v_exp_f32_e32 v154, v154
	v_fmamk_f32 v155, v155, 0x3fb8aa3b, v233
	v_add_f32_e32 v168, v150, v168
	v_exp_f32_e32 v155, v155
	v_fmamk_f32 v156, v156, 0x3fb8aa3b, v233
	v_add_f32_e32 v168, v151, v168
	v_exp_f32_e32 v156, v156
	v_fmamk_f32 v157, v157, 0x3fb8aa3b, v233
	v_add_f32_e32 v168, v152, v168
	v_exp_f32_e32 v157, v157
	v_fmamk_f32 v158, v158, 0x3fb8aa3b, v233
	v_add_f32_e32 v168, v153, v168
	v_exp_f32_e32 v158, v158
	v_fmamk_f32 v159, v159, 0x3fb8aa3b, v233
	v_add_f32_e32 v168, v154, v168
	v_exp_f32_e32 v159, v159
	v_fmamk_f32 v128, v128, 0x3fb8aa3b, v233
	v_add_f32_e32 v168, v155, v168
	v_exp_f32_e32 v128, v128
	v_fmamk_f32 v129, v129, 0x3fb8aa3b, v233
	v_add_f32_e32 v168, v156, v168
	v_exp_f32_e32 v129, v129
	v_fmamk_f32 v130, v130, 0x3fb8aa3b, v233
	v_add_f32_e32 v168, v157, v168
	v_exp_f32_e32 v130, v130
	v_fmamk_f32 v131, v131, 0x3fb8aa3b, v233
	v_add_f32_e32 v168, v158, v168
	v_exp_f32_e32 v131, v131
	v_fmamk_f32 v132, v132, 0x3fb8aa3b, v233
	v_add_f32_e32 v168, v159, v168
	v_exp_f32_e32 v132, v132
	v_fmamk_f32 v133, v133, 0x3fb8aa3b, v233
	v_add_f32_e32 v168, v128, v168
	v_exp_f32_e32 v133, v133
	v_fmamk_f32 v134, v134, 0x3fb8aa3b, v233
	v_add_f32_e32 v168, v129, v168
	v_exp_f32_e32 v134, v134
	v_fmamk_f32 v135, v135, 0x3fb8aa3b, v233
	v_add_f32_e32 v168, v130, v168
	v_exp_f32_e32 v135, v135
	v_fmamk_f32 v136, v136, 0x3fb8aa3b, v233
	v_add_f32_e32 v168, v131, v168
	v_exp_f32_e32 v136, v136
	v_fmamk_f32 v137, v137, 0x3fb8aa3b, v233
; __device__ __forceinline__ float bf2f(u16 v) { return __uint_as_float(((unsigned)v) << 16); }
; #define MFMA(a, b, c) __builtin_amdgcn_mfma_f32_32x32x16_bf16(a, b, c, 0, 0, 0)
; #define PK4N(PV, BASE, OUT) do { u32x4 w_ = {cvtpk(PV[BASE + 0], PV[BASE + 1]), cvtpk(PV[BASE + 2], PV[BASE + 3]), \
;     cvtpk(PV[BASE + 4], PV[BASE + 5]), cvtpk(PV[BASE + 6], PV[BASE + 7])}; OUT = *reinterpret_cast<bf16x8*>(&w_); } while (0)
; __device__ __forceinline__ void sm_fixed(f32x16& p0, f32x16& p1, float mC, float& l_reg, bf16x8& pa0, bf16x8& pa1, bf16x8& pa2, bf16x8& pa3) {
;   constexpr float C = 1.4426950408889634f;
; #pragma unroll
;   for (int r = 0; r < 16; ++r) p0[r] = __builtin_amdgcn_exp2f(fmaf(p0[r], C, -mC));
; #pragma unroll
;   for (int r = 0; r < 16; ++r) p1[r] = __builtin_amdgcn_exp2f(fmaf(p1[r], C, -mC));
;   float ps = 0;
; #pragma unroll
;   for (int r = 0; r < 16; ++r) ps += p0[r];
; #pragma unroll
;   for (int r = 0; r < 16; ++r) ps += p1[r];
;   { auto rr = __builtin_amdgcn_permlane32_swap(__float_as_uint(ps), __float_as_uint(ps), false, false);
;     ps = __uint_as_float(rr[0]) + __uint_as_float(rr[1]); }
;   l_reg += ps;
;     ...
;   PK4N(p0, 0, pa0); PK4N(p0, 8, pa1); PK4N(p1, 0, pa2); PK4N(p1, 8, pa3);
;     ...
; }
; #pragma unroll
;   for (int q = 0; q < 8; ++q) { const float f = bf2f((u16)v[q]); s += f * f; } return s; }
; __device__ __forceinline__ void att_qkt_p(f32x16& p0, f32x16& p1, const char* Kb, const bf16x8 (&qr)[2], const char* Qp, int koff, int ksw, int hi) {
;   p0 = f32x16{}; p1 = f32x16{};
; #pragma unroll
;   for (int d0 = 0; d0 < 4; ++d0) {
;     const int co = ((d0 * 2 + hi) ^ ksw) << 4;
;     const bf16x8 b0 = *(const bf16x8*)(Kb + koff + co);
;     const bf16x8 b1 = *(const bf16x8*)(Kb + koff + 4096 + co);
;     const bf16x8 qd = d0 < 2 ? qr[d0 & 1] : *(const bf16x8*)(Qp + (d0 - 2) * 4096);
;     p0 = MFMA(b0, qd, p0); p1 = MFMA(b1, qd, p1);
;   }
; }
	v_add_f32_e32 v168, v132, v168
	v_exp_f32_e32 v137, v137
	v_fmamk_f32 v138, v138, 0x3fb8aa3b, v233
	v_add_f32_e32 v168, v133, v168
	v_exp_f32_e32 v138, v138
	v_fmamk_f32 v139, v139, 0x3fb8aa3b, v233
	v_add_f32_e32 v168, v134, v168
	v_exp_f32_e32 v139, v139
	v_fmamk_f32 v140, v140, 0x3fb8aa3b, v233
	v_add_f32_e32 v168, v135, v168
	v_exp_f32_e32 v140, v140
	v_fmamk_f32 v141, v141, 0x3fb8aa3b, v233
	v_add_f32_e32 v168, v136, v168
	v_exp_f32_e32 v141, v141
	v_fmamk_f32 v142, v142, 0x3fb8aa3b, v233
	v_add_f32_e32 v168, v137, v168
	v_exp_f32_e32 v142, v142
	v_fmac_f32_e32 v233, 0x3fb8aa3b, v143
	v_add_f32_e32 v168, v138, v168
	v_exp_f32_e32 v143, v233
	v_add_f32_e32 v168, v139, v168
	v_add_f32_e32 v168, v140, v168
	v_add_f32_e32 v168, v141, v168
	v_add_f32_e32 v168, v142, v168
	v_add_f32_e32 v186, v143, v168
	v_mov_b32_e32 v187, v186
	s_nop 1
	v_permlane32_swap_b32_e32 v186, v187
	v_cvt_pk_bf16_f32 v176, v144, v145
	v_cvt_pk_bf16_f32 v177, v146, v147
	v_cvt_pk_bf16_f32 v178, v148, v149
	v_cvt_pk_bf16_f32 v179, v150, v151
	v_cvt_pk_bf16_f32 v180, v152, v153
	v_cvt_pk_bf16_f32 v181, v154, v155
	v_cvt_pk_bf16_f32 v182, v156, v157
	v_cvt_pk_bf16_f32 v183, v158, v159
	v_cvt_pk_bf16_f32 v168, v128, v129
	v_cvt_pk_bf16_f32 v169, v130, v131
	v_cvt_pk_bf16_f32 v170, v132, v133
	v_cvt_pk_bf16_f32 v171, v134, v135
	v_cvt_pk_bf16_f32 v172, v136, v137
	v_cvt_pk_bf16_f32 v173, v138, v139
	v_cvt_pk_bf16_f32 v174, v140, v141
	v_cvt_pk_bf16_f32 v175, v142, v143
	ds_read_b128 v[128:131], v198 offset:40960
	ds_read_b128 v[132:135], v198 offset:45056
	s_waitcnt lgkmcnt(1)
	v_mfma_f32_32x32x16_bf16 v[144:159], v[128:131], v[164:167], 0
	s_waitcnt lgkmcnt(0)
	v_mfma_f32_32x32x16_bf16 v[128:143], v[132:135], v[164:167], 0
	ds_read_b128 v[164:167], v199 offset:40960
	ds_read_b128 v[188:191], v199 offset:45056
	s_waitcnt lgkmcnt(0)
	v_mfma_f32_32x32x16_bf16 v[128:143], v[188:191], v[160:163], v[128:143]
	v_mfma_f32_32x32x16_bf16 v[144:159], v[164:167], v[160:163], v[144:159]
	ds_read_b128 v[160:163], v206 offset:40960
	ds_read_b128 v[164:167], v206 offset:45056
	ds_read_b128 v[188:191], v230
	s_waitcnt lgkmcnt(0)
	v_mfma_f32_32x32x16_bf16 v[128:143], v[164:167], v[188:191], v[128:143]
	v_mfma_f32_32x32x16_bf16 v[144:159], v[160:163], v[188:191], v[144:159]
	ds_read_b128 v[160:163], v207 offset:40960
	ds_read_b128 v[164:167], v207 offset:45056
	ds_read_b128 v[188:191], v230 offset:4096
	s_waitcnt lgkmcnt(0)
	v_mfma_f32_32x32x16_bf16 v[128:143], v[164:167], v[188:191], v[128:143]
	v_mfma_f32_32x32x16_bf16 v[144:159], v[160:163], v[188:191], v[144:159]
	s_nop 10
	v_fmamk_f32 v128, v128, 0x3fb8aa3b, v231
	v_exp_f32_e32 v162, v128
	v_fmamk_f32 v128, v129, 0x3fb8aa3b, v231
	v_exp_f32_e32 v163, v128
	v_fmamk_f32 v128, v130, 0x3fb8aa3b, v231
	v_exp_f32_e32 v164, v128
	v_fmamk_f32 v128, v131, 0x3fb8aa3b, v231
	v_exp_f32_e32 v165, v128
	v_fmamk_f32 v128, v132, 0x3fb8aa3b, v231
	v_exp_f32_e32 v166, v128
	v_fmamk_f32 v128, v133, 0x3fb8aa3b, v231
	v_exp_f32_e32 v167, v128
	v_fmamk_f32 v128, v134, 0x3fb8aa3b, v231
	v_exp_f32_e32 v188, v128
	v_fmamk_f32 v128, v135, 0x3fb8aa3b, v231
	v_exp_f32_e32 v189, v128
	v_fmamk_f32 v128, v136, 0x3fb8aa3b, v231
	v_exp_f32_e32 v190, v128
	v_fmamk_f32 v128, v137, 0x3fb8aa3b, v231
	v_fmamk_f32 v144, v144, 0x3fb8aa3b, v231
	v_exp_f32_e32 v191, v128
	v_fmamk_f32 v128, v138, 0x3fb8aa3b, v231
	v_exp_f32_e32 v160, v144
	v_fmamk_f32 v144, v145, 0x3fb8aa3b, v231
	v_exp_f32_e32 v192, v128
	v_fmamk_f32 v128, v139, 0x3fb8aa3b, v231
	v_exp_f32_e32 v145, v144
	v_fmamk_f32 v144, v146, 0x3fb8aa3b, v231
	v_exp_f32_e32 v193, v128
	v_fmamk_f32 v128, v140, 0x3fb8aa3b, v231
	v_exp_f32_e32 v161, v144
	v_fmamk_f32 v144, v147, 0x3fb8aa3b, v231
	v_exp_f32_e32 v194, v128
	v_fmamk_f32 v128, v141, 0x3fb8aa3b, v231
	v_exp_f32_e32 v147, v144
	v_fmamk_f32 v144, v148, 0x3fb8aa3b, v231
	v_exp_f32_e32 v195, v128
	v_fmamk_f32 v128, v142, 0x3fb8aa3b, v231
	v_exp_f32_e32 v148, v144
	v_fmamk_f32 v144, v149, 0x3fb8aa3b, v231
	v_exp_f32_e32 v196, v128
	v_add_f32_e32 v128, 0, v160
	v_exp_f32_e32 v149, v144
	v_fmamk_f32 v144, v150, 0x3fb8aa3b, v231
	v_add_f32_e32 v128, v145, v128
	v_exp_f32_e32 v150, v144
	v_fmamk_f32 v144, v151, 0x3fb8aa3b, v231
	v_add_f32_e32 v128, v161, v128
	v_exp_f32_e32 v151, v144
	v_fmamk_f32 v144, v152, 0x3fb8aa3b, v231
	v_add_f32_e32 v128, v147, v128
	v_exp_f32_e32 v152, v144
	v_fmamk_f32 v144, v153, 0x3fb8aa3b, v231
	v_add_f32_e32 v128, v148, v128
	v_exp_f32_e32 v153, v144
	v_fmamk_f32 v144, v154, 0x3fb8aa3b, v231
	v_add_f32_e32 v128, v149, v128
	v_exp_f32_e32 v154, v144
	v_fmamk_f32 v144, v155, 0x3fb8aa3b, v231
	v_add_f32_e32 v128, v150, v128
	v_exp_f32_e32 v155, v144
	v_fmamk_f32 v144, v156, 0x3fb8aa3b, v231
	v_add_f32_e32 v128, v151, v128
	v_exp_f32_e32 v156, v144
	v_fmamk_f32 v144, v157, 0x3fb8aa3b, v231
	v_add_f32_e32 v128, v152, v128
	v_exp_f32_e32 v157, v144
	v_fmamk_f32 v144, v158, 0x3fb8aa3b, v231
	v_add_f32_e32 v128, v153, v128
	v_exp_f32_e32 v158, v144
	v_fmamk_f32 v144, v159, 0x3fb8aa3b, v231
	v_add_f32_e32 v128, v154, v128
	v_exp_f32_e32 v159, v144
	v_add_f32_e32 v128, v155, v128
	v_add_f32_e32 v128, v156, v128
	v_add_f32_e32 v128, v157, v128
	v_add_f32_e32 v128, v158, v128
	v_add_f32_e32 v128, v159, v128
	v_add_f32_e32 v128, v162, v128
	v_add_f32_e32 v128, v163, v128
	v_add_f32_e32 v128, v164, v128
	v_add_f32_e32 v128, v165, v128
	v_add_f32_e32 v128, v166, v128
	v_add_f32_e32 v128, v167, v128
	v_add_f32_e32 v128, v188, v128
	v_add_f32_e32 v128, v189, v128
	v_add_f32_e32 v128, v190, v128
	v_add_f32_e32 v128, v191, v128
	v_fmac_f32_e32 v231, 0x3fb8aa3b, v143
	v_add_f32_e32 v128, v192, v128
	v_exp_f32_e32 v143, v231
	v_add_f32_e32 v128, v193, v128
	v_add_f32_e32 v128, v194, v128
	v_add_f32_e32 v128, v195, v128
	v_add_f32_e32 v128, v196, v128
	v_add_f32_e32 v144, v143, v128
	v_mov_b32_e32 v146, v144
	s_nop 1
	v_permlane32_swap_b32_e32 v144, v146
	v_cvt_pk_bf16_f32 v128, v160, v145
	v_cvt_pk_bf16_f32 v129, v161, v147
	v_cvt_pk_bf16_f32 v130, v148, v149
	v_cvt_pk_bf16_f32 v131, v150, v151
	v_cvt_pk_bf16_f32 v132, v152, v153
	v_cvt_pk_bf16_f32 v133, v154, v155
	v_cvt_pk_bf16_f32 v134, v156, v157
	v_cvt_pk_bf16_f32 v135, v158, v159
	v_cvt_pk_bf16_f32 v136, v162, v163
	v_cvt_pk_bf16_f32 v137, v164, v165
	v_cvt_pk_bf16_f32 v138, v166, v167
	v_cvt_pk_bf16_f32 v139, v188, v189
	v_cvt_pk_bf16_f32 v140, v190, v191
	v_cvt_pk_bf16_f32 v141, v192, v193
	v_cvt_pk_bf16_f32 v142, v194, v195
	v_cvt_pk_bf16_f32 v143, v196, v143
	ds_read_b64_tr_b16 v[148:149], v185 offset:0
	ds_read_b64_tr_b16 v[150:151], v185 offset:0x800
	ds_read_b64_tr_b16 v[152:153], v185 offset:0x1000
	ds_read_b64_tr_b16 v[154:155], v185 offset:0x1800
	s_waitcnt lgkmcnt(0)
; __device__ __forceinline__ int crow(int r, int hi) { return (r & 3) + 8 * (r >> 2) + 4 * hi; }
; #define SBAR() __builtin_amdgcn_sched_barrier(0)
; #define MFMA(a, b, c) __builtin_amdgcn_mfma_f32_32x32x16_bf16(a, b, c, 0, 0, 0)
; template <int D0> __device__ __forceinline__ void pv_two(f32x16& oa, f32x16& ob, int vb, bf16x8 a0, bf16x8 a1, bf16x8 a2, bf16x8 a3,
;                                                          bf16x8 b0, bf16x8 b1, bf16x8 b2, bf16x8 b3) {
;     ...
;   { const s16x4 l0 = tr_read<v_rd_off(D0, 0, 0)>(vb), h0 = tr_read<v_rd_off(D0, 0, 1)>(vb), l1 = tr_read<v_rd_off(D0, 1, 0)>(vb), h1 = tr_read<v_rd_off(D0, 1, 1)>(vb);
;     asm volatile("s_waitcnt lgkmcnt(0)" ::: "memory"); SBAR();
;     const bf16x8 v0 = PKV(l0, h0), v1 = PKV(l1, h1);
;     oa = MFMA(a0, v0, oa); ob = MFMA(b0, v0, ob); oa = MFMA(a1, v1, oa); ob = MFMA(b1, v1, ob); }
;   { const s16x4 l2 = tr_read<v_rd_off(D0, 2, 0)>(vb), h2 = tr_read<v_rd_off(D0, 2, 1)>(vb), l3 = tr_read<v_rd_off(D0, 3, 0)>(vb), h3 = tr_read<v_rd_off(D0, 3, 1)>(vb);
;     asm volatile("s_waitcnt lgkmcnt(0)" ::: "memory"); SBAR();
;     const bf16x8 v2 = PKV(l2, h2), v3 = PKV(l3, h3);
;     oa = MFMA(a2, v2, oa); ob = MFMA(b2, v2, ob); oa = MFMA(a3, v3, oa); ob = MFMA(b3, v3, ob); }
;     ...
; }
; __device__ __forceinline__ void attn_item(const P& p, int layer, int item, char* lds) {
;     ...
;   float r1[16], r2[16];
;   if (hi == 0) li_l[r32] = l1;
;   asm volatile("s_waitcnt lgkmcnt(0)" ::: "memory");
; #pragma unroll
;   for (int r = 0; r < 16; ++r) r1[r] = 1.f / li_l[crow(r, hi)];
;   asm volatile("s_waitcnt lgkmcnt(0)" ::: "memory");
;   if (hi == 0) li_l[r32] = l2;
;   asm volatile("s_waitcnt lgkmcnt(0)" ::: "memory");
; #pragma unroll
;   for (int r = 0; r < 16; ++r) r2[r] = lam / li_l[crow(r, hi)];
	s_nop 0
	v_mfma_f32_32x32x16_bf16 v[64:79], v[176:179], v[148:151], v[64:79]
	v_mfma_f32_32x32x16_bf16 v[0:15], v[128:131], v[148:151], v[0:15]
	ds_read_b64_tr_b16 v[148:149], v185 offset:0x2000
	ds_read_b64_tr_b16 v[150:151], v185 offset:0x2800
	v_mfma_f32_32x32x16_bf16 v[64:79], v[180:183], v[152:155], v[64:79]
	v_mfma_f32_32x32x16_bf16 v[0:15], v[132:135], v[152:155], v[0:15]
	ds_read_b64_tr_b16 v[152:153], v185 offset:0x3000
	ds_read_b64_tr_b16 v[154:155], v185 offset:0x3800
	s_waitcnt lgkmcnt(0)
	v_mfma_f32_32x32x16_bf16 v[64:79], v[168:171], v[148:151], v[64:79]
	v_mfma_f32_32x32x16_bf16 v[0:15], v[136:139], v[148:151], v[0:15]
	ds_read_b64_tr_b16 v[148:149], v185 offset:0x200
	ds_read_b64_tr_b16 v[150:151], v185 offset:0xa00
	v_mfma_f32_32x32x16_bf16 v[64:79], v[172:175], v[152:155], v[64:79]
	v_mfma_f32_32x32x16_bf16 v[0:15], v[140:143], v[152:155], v[0:15]
	ds_read_b64_tr_b16 v[152:153], v185 offset:0x1200
	ds_read_b64_tr_b16 v[154:155], v185 offset:0x1a00
	s_waitcnt lgkmcnt(0)
	v_mfma_f32_32x32x16_bf16 v[80:95], v[176:179], v[148:151], v[80:95]
	v_mfma_f32_32x32x16_bf16 v[16:31], v[128:131], v[148:151], v[16:31]
	ds_read_b64_tr_b16 v[148:149], v185 offset:0x2200
	ds_read_b64_tr_b16 v[150:151], v185 offset:0x2a00
	v_mfma_f32_32x32x16_bf16 v[80:95], v[180:183], v[152:155], v[80:95]
	v_mfma_f32_32x32x16_bf16 v[16:31], v[132:135], v[152:155], v[16:31]
	ds_read_b64_tr_b16 v[152:153], v185 offset:0x3200
	ds_read_b64_tr_b16 v[154:155], v185 offset:0x3a00
	s_waitcnt lgkmcnt(0)
	v_mfma_f32_32x32x16_bf16 v[80:95], v[168:171], v[148:151], v[80:95]
	v_mfma_f32_32x32x16_bf16 v[16:31], v[136:139], v[148:151], v[16:31]
	ds_read_b64_tr_b16 v[148:149], v185 offset:0x400
	ds_read_b64_tr_b16 v[150:151], v185 offset:0xc00
	v_mfma_f32_32x32x16_bf16 v[80:95], v[172:175], v[152:155], v[80:95]
	v_mfma_f32_32x32x16_bf16 v[16:31], v[140:143], v[152:155], v[16:31]
	ds_read_b64_tr_b16 v[152:153], v185 offset:0x1400
	ds_read_b64_tr_b16 v[154:155], v185 offset:0x1c00
	s_waitcnt lgkmcnt(0)
	v_mfma_f32_32x32x16_bf16 v[96:111], v[176:179], v[148:151], v[96:111]
	v_mfma_f32_32x32x16_bf16 v[32:47], v[128:131], v[148:151], v[32:47]
	ds_read_b64_tr_b16 v[148:149], v185 offset:0x2400
	ds_read_b64_tr_b16 v[150:151], v185 offset:0x2c00
	v_mfma_f32_32x32x16_bf16 v[96:111], v[180:183], v[152:155], v[96:111]
	v_mfma_f32_32x32x16_bf16 v[32:47], v[132:135], v[152:155], v[32:47]
	ds_read_b64_tr_b16 v[152:153], v185 offset:0x3400
	ds_read_b64_tr_b16 v[154:155], v185 offset:0x3c00
	s_waitcnt lgkmcnt(0)
	v_mfma_f32_32x32x16_bf16 v[96:111], v[168:171], v[148:151], v[96:111]
	v_mfma_f32_32x32x16_bf16 v[32:47], v[136:139], v[148:151], v[32:47]
	ds_read_b64_tr_b16 v[148:149], v185 offset:0x600
	ds_read_b64_tr_b16 v[150:151], v185 offset:0xe00
	v_mfma_f32_32x32x16_bf16 v[96:111], v[172:175], v[152:155], v[96:111]
	v_mfma_f32_32x32x16_bf16 v[32:47], v[140:143], v[152:155], v[32:47]
	ds_read_b64_tr_b16 v[152:153], v185 offset:0x1600
	ds_read_b64_tr_b16 v[154:155], v185 offset:0x1e00
	s_waitcnt lgkmcnt(0)
	v_mfma_f32_32x32x16_bf16 v[112:127], v[176:179], v[148:151], v[112:127]
	v_mfma_f32_32x32x16_bf16 v[48:63], v[128:131], v[148:151], v[48:63]
	ds_read_b64_tr_b16 v[128:129], v185 offset:0x2600
	ds_read_b64_tr_b16 v[130:131], v185 offset:0x2e00
	ds_read_b64_tr_b16 v[148:149], v185 offset:0x3600
	ds_read_b64_tr_b16 v[150:151], v185 offset:0x3e00
	s_waitcnt lgkmcnt(0)
	v_mfma_f32_32x32x16_bf16 v[112:127], v[180:183], v[152:155], v[112:127]
	v_mfma_f32_32x32x16_bf16 v[48:63], v[132:135], v[152:155], v[48:63]
	v_mfma_f32_32x32x16_bf16 v[112:127], v[168:171], v[128:131], v[112:127]
	v_cmp_gt_u32_e32 vcc, 32, v228
	v_lshl_add_u32 v147, v226, 2, v184
	v_mfma_f32_32x32x16_bf16 v[48:63], v[136:139], v[128:131], v[48:63]
	v_mfma_f32_32x32x16_bf16 v[112:127], v[172:175], v[148:151], v[112:127]
	v_mfma_f32_32x32x16_bf16 v[48:63], v[140:143], v[148:151], v[48:63]
	s_and_saveexec_b64 s[6:7], vcc
	v_add_f32_e32 v128, v186, v187
	v_add_f32_e32 v128, v204, v128
	ds_write_b32 v147, v128
	s_or_b64 exec, exec, s[6:7]
	s_waitcnt lgkmcnt(0)
	v_add_u32_e32 v145, v184, v200
	ds_read_b128 v[128:131], v145
	ds_read_b128 v[132:135], v145 offset:32
	ds_read_b128 v[136:139], v145 offset:64
	ds_read_b128 v[140:143], v145 offset:96
	s_waitcnt lgkmcnt(0)
	s_mov_b64 s[6:7], exec
	s_and_b64 s[18:19], s[6:7], vcc
	v_mov_b32_e32 v206, 0x14000
	v_mov_b32_e32 v207, 0x68000
	v_mov_b32_e32 v208, 0x16000
	v_mov_b32_e32 v209, 0x66000
	v_mov_b32_e32 v210, 0x18000
	v_mov_b32_e32 v211, 0x64000
	v_mov_b32_e32 v212, 0x1a000
	v_mov_b32_e32 v213, 0x62000
	v_mov_b32_e32 v214, 0x1c000
	v_mov_b32_e32 v216, 0x60000
	v_mov_b32_e32 v218, 0x1e000
	v_mov_b32_e32 v219, 0x5e000
	v_mov_b32_e32 v220, 0x20000
	v_mov_b32_e32 v221, 0x5c000
	v_mov_b32_e32 v228, 0x22000
	v_mov_b32_e32 v230, 0x5a000
	v_mov_b32_e32 v231, 0x24000
	v_mov_b32_e32 v232, 0x58000
	v_mov_b32_e32 v233, 0x26000
	v_mov_b32_e32 v234, 0x56000
	v_mov_b32_e32 v235, 0x28000
	v_mov_b32_e32 v236, 0x54000
	v_mov_b32_e32 v237, 0x2a000
	v_mov_b32_e32 v238, 0x52000
	v_mov_b32_e32 v239, 0x2c000
	v_mov_b32_e32 v240, 0x50000
	v_mov_b32_e32 v241, 0x2e000
	v_mov_b32_e32 v242, 0x4e000
	v_mov_b32_e32 v243, 0x30000
	v_mov_b32_e32 v244, 0x4c000
	v_mov_b32_e32 v245, 0x32000
	v_mov_b32_e32 v246, 0x4a000
	v_mov_b32_e32 v247, 0x34000
	v_mov_b32_e32 v248, 0x48000
	v_mov_b32_e32 v249, 0x36000
	v_mov_b32_e32 v179, 0x46000
	v_mov_b32_e32 v181, 0x38000
	s_mov_b64 exec, s[18:19]
	s_cbranch_execz .LBB0_270
	v_add_f32_e32 v144, v144, v146
	v_add_f32_e32 v144, v205, v144
	ds_write_b32 v147, v144
	s_branch .LBB0_270
